# context differential / context attention units: flat->global and LDS reads issued 4 ahead with counted lgkmcnt (17 MFMA regions)
# speedup vs baseline: 1.0047x; 1.0047x over previous
.LBB0_830:
	s_ashr_i32 s2, s16, 3
	s_ashr_i32 s3, s2, 31
	s_bfe_u32 s17, s16, 0x20001
	s_lshl_b64 s[4:5], s[2:3], 8
	s_mul_i32 s7, s2, 0x208000
	s_mul_hi_i32 s6, s2, 0x208000
	s_add_u32 s7, s12, s7
	s_addc_u32 s8, s13, s6
	s_lshl_b32 s40, s17, 8
	s_add_u32 s6, s7, s40
	s_addc_u32 s7, s8, 0
	s_add_u32 s20, s6, 0xc00
	s_addc_u32 s21, s7, 0
	s_lshl_b32 s8, s17, 22
	s_add_u32 s8, s85, s8
	s_addc_u32 s9, s82, 0
	s_lshl_b64 s[2:3], s[2:3], 9
	s_add_u32 s8, s8, s2
	v_mov_b32_e32 v172, v206
	s_addc_u32 s9, s9, s3
	s_and_b32 s2, s11, 0x80
	v_mov_b32_e32 v10, v206
	v_readfirstlane_b32 s10, v172
	s_bfe_u32 s18, s10, 0x20006
	v_and_or_b32 v0, v172, 31, s2
	v_lshl_or_b32 v0, s18, 5, v0
	v_or_b32_e32 v174, s4, v0
	v_mov_b64_e32 v[0:1], s[12:13]
	s_ashr_i32 s19, s10, 8
	v_mad_u64_u32 v[146:147], s[2:3], v174, s79, v[0:1]
	v_mad_i32_i24 v147, s5, v211, v147
	s_lshl_b32 s2, s19, 6
	v_lshl_add_u64 v[0:1], v[146:147], 0, s[40:41]
	s_ashr_i32 s3, s2, 31
	v_lshl_add_u64 v[0:1], s[2:3], 1, v[0:1]
	v_lshrrev_b32_e32 v2, 1, v10
	v_and_b32_e32 v192, 16, v2
	v_lshl_add_u64 v[0:1], v[0:1], 0, v[192:193]
	v_lshlrev_b32_e32 v25, 4, v10
	global_load_dwordx4 v[124:127], v[0:1], off offset:2048
	global_load_dwordx4 v[120:123], v[0:1], off offset:2080
	global_load_dwordx4 v[116:119], v[0:1], off offset:2112
	global_load_dwordx4 v[112:115], v[0:1], off offset:2144
	v_and_b32_e32 v0, 0x70, v25
	v_mov_b32_e32 v1, v193
	v_lshl_add_u64 v[0:1], s[8:9], 0, v[0:1]
	s_mov_b64 s[8:9], 0x1000000
	v_lshl_add_u64 v[12:13], v[0:1], 0, s[8:9]
	v_ashrrev_i32_e32 v0, 31, v10
	v_lshrrev_b32_e32 v0, 28, v0
	v_add_u32_e32 v2, v10, v0
	v_ashrrev_i32_e32 v128, 4, v2
	v_and_b32_e32 v2, -16, v2
	v_add_u32_e32 v14, 0x200, v10
	v_readfirstlane_b32 s4, v10
	v_and_b32_e32 v32, 31, v10
	v_lshlrev_b32_e32 v24, 3, v10
	v_sub_u32_e32 v26, v10, v2
	v_ashrrev_i32_e32 v18, 3, v10
	v_ashrrev_i32_e32 v10, 31, v14
	v_lshrrev_b32_e32 v10, 28, v10
	v_lshlrev_b32_e32 v96, 3, v26
	v_add_u32_e32 v10, v14, v10
	v_mov_b64_e32 v[8:9], s[6:7]
	v_ashrrev_i32_e32 v97, 31, v96
	v_ashrrev_i32_e32 v19, 31, v18
	v_ashrrev_i32_e32 v129, 4, v10
	v_and_b32_e32 v10, -16, v10
	v_mad_i64_i32 v[0:1], s[8:9], v128, s79, v[8:9]
	v_lshlrev_b64 v[16:17], 1, v[96:97]
	v_lshlrev_b64 v[4:5], 15, v[18:19]
	v_sub_u32_e32 v19, v14, v10
	v_lshl_add_u64 v[0:1], v[0:1], 0, v[16:17]
	v_lshlrev_b32_e32 v100, 3, v19
	global_load_dwordx4 v[0:3], v[0:1], off offset:3072
	v_ashrrev_i32_e32 v101, 31, v100
	v_mad_i64_i32 v[8:9], s[8:9], v129, s79, v[8:9]
	v_lshlrev_b64 v[20:21], 1, v[100:101]
	v_ashrrev_i32_e32 v22, 3, v14
	v_lshl_add_u64 v[98:99], v[12:13], 0, v[4:5]
	v_lshl_add_u64 v[8:9], v[8:9], 0, v[20:21]
	v_ashrrev_i32_e32 v23, 31, v22
	global_load_dwordx4 v[4:7], v[98:99], off
	v_lshlrev_b64 v[14:15], 15, v[22:23]
	global_load_dwordx4 v[8:11], v[8:9], off offset:3072
	v_lshl_add_u64 v[102:103], v[12:13], 0, v[14:15]
	global_load_dwordx4 v[12:15], v[102:103], off
	v_and_b32_e32 v23, 0x60, v25
	v_and_b32_e32 v24, 8, v24
	s_movk_i32 s8, 0x110
	v_add3_u32 v130, 0, v23, v24
	v_mul_lo_u32 v23, v128, s8
	v_add_u32_e32 v23, 0, v23
	v_lshlrev_b32_e32 v24, 4, v26
	s_cmpk_gt_i32 s4, 0xff
	v_add_u32_e32 v177, v23, v24
	s_cselect_b64 s[2:3], -1, 0
	s_cmpk_lt_i32 s4, 0x100
	v_mul_lo_u32 v131, v18, s80
	v_mov_b32_e32 v173, s5
	s_cselect_b64 s[4:5], -1, 0
	v_add_u32_e32 v18, v130, v131
	v_add_u32_e32 v178, 0x8800, v18
	v_mul_lo_u32 v132, v22, s80
	v_mul_u32_u24_e32 v22, 0x110, v32
	s_mov_b32 s54, s41
	s_mov_b32 s55, s41
	s_mov_b32 s40, s41
	s_mov_b32 s42, s41
	s_mov_b32 s43, s41
	s_mov_b32 s44, s41
	s_mov_b32 s45, s41
	s_mov_b32 s46, s41
	s_mov_b32 s47, s41
	s_mov_b32 s48, s41
	s_mov_b32 s49, s41
	s_mov_b32 s50, s41
	s_mov_b32 s51, s41
	s_mov_b32 s52, s41
	s_mov_b32 s53, s41
	v_mov_b64_e32 v[62:63], s[54:55]
	v_add_u32_e32 v33, 0, v192
	v_mov_b64_e32 v[48:49], s[40:41]
	v_mov_b64_e32 v[60:61], s[52:53]
	v_mov_b64_e32 v[58:59], s[50:51]
	v_mov_b64_e32 v[56:57], s[48:49]
	v_mov_b64_e32 v[54:55], s[46:47]
	v_mov_b64_e32 v[52:53], s[44:45]
	v_mov_b64_e32 v[50:51], s[42:43]
	s_waitcnt vmcnt(0) lgkmcnt(0)
	ds_write_b128 v177, v[0:3]
	v_mul_lo_u32 v0, v129, s8
	v_add_u32_e32 v0, 0, v0
	v_lshlrev_b32_e32 v1, 4, v19
	s_add_u32 s8, s6, 0x82c00
	v_add_u32_e32 v180, v0, v1
	s_addc_u32 s9, s7, 0
	v_add_u32_e32 v19, v130, v132
	v_add_u32_e32 v179, 0x8800, v19
	ds_write2_b64 v178, v[4:5], v[6:7] offset1:2
	s_add_u32 s6, s6, 0x104c00
	ds_write_b128 v180, v[8:11]
	v_mov_b64_e32 v[8:9], s[8:9]
	v_mad_i64_i32 v[0:1], s[8:9], v128, s79, v[8:9]
	ds_write2_b64 v179, v[12:13], v[14:15] offset1:2
	v_lshl_add_u64 v[0:1], v[0:1], 0, v[16:17]
	v_mad_i64_i32 v[8:9], s[8:9], v129, s79, v[8:9]
	global_load_dwordx4 v[0:3], v[0:1], off
	s_nop 0
	global_load_dwordx4 v[4:7], v[98:99], off offset:128
	v_lshl_add_u64 v[8:9], v[8:9], 0, v[20:21]
	global_load_dwordx4 v[8:11], v[8:9], off
	s_nop 0
	global_load_dwordx4 v[12:15], v[102:103], off offset:128
	s_waitcnt lgkmcnt(0)
	s_barrier
	s_barrier
	s_addc_u32 s7, s7, 0
	s_and_b64 vcc, exec, s[2:3]
	s_waitcnt vmcnt(0)
	ds_write_b128 v177, v[0:3] offset:17408
	v_add_u32_e32 v0, 0xd000, v18
	ds_write2_b64 v0, v[4:5], v[6:7] offset1:2
	ds_write_b128 v180, v[8:11] offset:17408
	v_add_u32_e32 v0, 0xd000, v19
	ds_write2_b64 v0, v[12:13], v[14:15] offset1:2
	v_mov_b64_e32 v[0:1], s[6:7]
	v_mad_i64_i32 v[2:3], s[6:7], v128, s79, v[0:1]
	v_mad_i64_i32 v[0:1], s[6:7], v129, s79, v[0:1]
	v_lshl_add_u64 v[2:3], v[2:3], 0, v[16:17]
	v_lshl_add_u64 v[0:1], v[0:1], 0, v[20:21]
	global_load_dwordx4 v[76:79], v[2:3], off
	global_load_dwordx4 v[68:71], v[98:99], off offset:256
	global_load_dwordx4 v[72:75], v[0:1], off
	global_load_dwordx4 v[64:67], v[102:103], off offset:256
	s_lshl_b32 s6, s19, 7
	s_add_i32 s6, s6, 0
	v_add3_u32 v176, s6, v22, v192
	ds_read_b128 v[240:243], v176
	ds_read_b128 v[244:247], v176 offset:8704
	ds_read_b128 v[248:251], v176 offset:32
	ds_read_b128 v[252:255], v176 offset:8736
	s_waitcnt lgkmcnt(3)
	v_mfma_f32_32x32x16_bf16 v[0:15], v[240:243], v[124:127], 0
	ds_read_b128 v[240:243], v176 offset:64
	s_waitcnt lgkmcnt(3)
	v_mfma_f32_32x32x16_bf16 v[16:31], v[244:247], v[124:127], 0
	ds_read_b128 v[244:247], v176 offset:8768
	s_waitcnt lgkmcnt(3)
	v_mfma_f32_32x32x16_bf16 v[0:15], v[248:251], v[120:123], v[0:15]
	ds_read_b128 v[248:251], v176 offset:96
	s_waitcnt lgkmcnt(3)
	v_mfma_f32_32x32x16_bf16 v[16:31], v[252:255], v[120:123], v[16:31]
	ds_read_b128 v[252:255], v176 offset:8800
	s_waitcnt lgkmcnt(3)
	v_mfma_f32_32x32x16_bf16 v[0:15], v[240:243], v[116:119], v[0:15]
	s_waitcnt lgkmcnt(2)
	v_mfma_f32_32x32x16_bf16 v[16:31], v[244:247], v[116:119], v[16:31]
	s_waitcnt lgkmcnt(1)
	v_mfma_f32_32x32x16_bf16 v[0:15], v[248:251], v[112:115], v[0:15]
	s_waitcnt lgkmcnt(0)
	v_mfma_f32_32x32x16_bf16 v[16:31], v[252:255], v[112:115], v[16:31]
	s_nop 11
	v_max_f32_e32 v34, v1, v1
	v_max_f32_e32 v35, v0, v0
	v_max_f32_e32 v34, v35, v34
	v_max3_f32 v35, v2, v3, v17
	v_max3_f32 v34, v34, v16, v18
	v_max3_f32 v34, v34, v19, v4
	v_max3_f32 v35, v35, v6, v7
	v_max3_f32 v34, v34, v5, v20
	v_max3_f32 v35, v35, v22, v23
	v_max3_f32 v34, v34, v21, v8
	v_max3_f32 v35, v35, v10, v11
	v_max3_f32 v34, v34, v9, v24
	v_max3_f32 v35, v35, v26, v27
	v_max3_f32 v34, v34, v25, v12
	v_max3_f32 v35, v35, v14, v15
	v_max3_f32 v34, v34, v13, v28
	v_max3_f32 v35, v35, v30, v31
	v_max3_f32 v34, v34, v29, v35
	v_mov_b32_e32 v35, v34
	s_nop 1
	v_permlane32_swap_b32_e32 v34, v35
	v_max_f32_e32 v35, v35, v35
	v_max_f32_e32 v34, v34, v34
	v_max_f32_e32 v181, v34, v35
	v_sub_f32_e32 v0, v0, v181
	v_sub_f32_e32 v16, v16, v181
	v_sub_f32_e32 v1, v1, v181
	v_sub_f32_e32 v17, v17, v181
	v_sub_f32_e32 v2, v2, v181
	v_sub_f32_e32 v18, v18, v181
	v_sub_f32_e32 v3, v3, v181
	v_sub_f32_e32 v19, v19, v181
	v_sub_f32_e32 v4, v4, v181
	v_sub_f32_e32 v20, v20, v181
	v_sub_f32_e32 v5, v5, v181
	v_sub_f32_e32 v21, v21, v181
	v_sub_f32_e32 v6, v6, v181
	v_sub_f32_e32 v22, v22, v181
	v_sub_f32_e32 v7, v7, v181
	v_sub_f32_e32 v23, v23, v181
	v_sub_f32_e32 v8, v8, v181
	v_sub_f32_e32 v24, v24, v181
	v_sub_f32_e32 v9, v9, v181
	v_sub_f32_e32 v25, v25, v181
	v_sub_f32_e32 v10, v10, v181
	v_sub_f32_e32 v26, v26, v181
	v_sub_f32_e32 v11, v11, v181
	v_sub_f32_e32 v27, v27, v181
	v_sub_f32_e32 v12, v12, v181
	v_sub_f32_e32 v28, v28, v181
	v_sub_f32_e32 v13, v13, v181
	v_sub_f32_e32 v29, v29, v181
	v_sub_f32_e32 v14, v14, v181
	v_sub_f32_e32 v30, v30, v181
	v_sub_f32_e32 v15, v15, v181
	v_sub_f32_e32 v31, v31, v181
	v_exp_f32_e32 v104, v0
	v_exp_f32_e32 v105, v1
	v_exp_f32_e32 v106, v16
	v_exp_f32_e32 v107, v17
	v_exp_f32_e32 v108, v2
	v_exp_f32_e32 v109, v3
	v_exp_f32_e32 v110, v18
	v_exp_f32_e32 v111, v19
	v_exp_f32_e32 v148, v4
	v_exp_f32_e32 v149, v5
	v_exp_f32_e32 v150, v20
	v_exp_f32_e32 v151, v21
	v_exp_f32_e32 v152, v6
	v_exp_f32_e32 v153, v7
	v_exp_f32_e32 v154, v22
	v_exp_f32_e32 v155, v23
	v_exp_f32_e32 v156, v8
	v_exp_f32_e32 v157, v9
	v_exp_f32_e32 v158, v24
	v_exp_f32_e32 v159, v25
	v_exp_f32_e32 v160, v10
	v_exp_f32_e32 v161, v11
	v_exp_f32_e32 v162, v26
	v_exp_f32_e32 v163, v27
	v_exp_f32_e32 v164, v12
	v_exp_f32_e32 v165, v13
	v_exp_f32_e32 v166, v28
	v_exp_f32_e32 v167, v29
	v_exp_f32_e32 v168, v14
	v_exp_f32_e32 v169, v15
	v_exp_f32_e32 v170, v30
	v_exp_f32_e32 v171, v31
	v_mul_u32_u24_e32 v0, 0x90, v32
	v_add_u32_e32 v175, v33, v0
	v_mov_b64_e32 v[32:33], v[48:49]
	v_mov_b64_e32 v[16:17], v[48:49]
	v_mov_b64_e32 v[0:1], v[48:49]
	v_cvt_pk_bf16_f32 v84, v104, v105
	v_cvt_pk_bf16_f32 v85, v108, v109
	v_cvt_pk_bf16_f32 v86, v148, v149
	v_cvt_pk_bf16_f32 v87, v152, v153
	v_cvt_pk_bf16_f32 v80, v106, v107
	v_cvt_pk_bf16_f32 v81, v110, v111
	v_cvt_pk_bf16_f32 v82, v150, v151
	v_cvt_pk_bf16_f32 v83, v154, v155
	v_cvt_pk_bf16_f32 v92, v156, v157
	v_cvt_pk_bf16_f32 v93, v160, v161
	v_cvt_pk_bf16_f32 v94, v164, v165
	v_cvt_pk_bf16_f32 v95, v168, v169
	v_cvt_pk_bf16_f32 v88, v158, v159
	v_cvt_pk_bf16_f32 v89, v162, v163
	v_cvt_pk_bf16_f32 v90, v166, v167
	v_cvt_pk_bf16_f32 v91, v170, v171
	v_mov_b64_e32 v[34:35], v[50:51]
	v_mov_b64_e32 v[36:37], v[52:53]
	v_mov_b64_e32 v[38:39], v[54:55]
	v_mov_b64_e32 v[40:41], v[56:57]
	v_mov_b64_e32 v[42:43], v[58:59]
	v_mov_b64_e32 v[44:45], v[60:61]
	v_mov_b64_e32 v[46:47], v[62:63]
	v_mov_b64_e32 v[18:19], v[50:51]
	v_mov_b64_e32 v[20:21], v[52:53]
	v_mov_b64_e32 v[22:23], v[54:55]
	v_mov_b64_e32 v[24:25], v[56:57]
	v_mov_b64_e32 v[26:27], v[58:59]
	v_mov_b64_e32 v[28:29], v[60:61]
	v_mov_b64_e32 v[30:31], v[62:63]
	v_mov_b64_e32 v[2:3], v[50:51]
	v_mov_b64_e32 v[4:5], v[52:53]
	v_mov_b64_e32 v[6:7], v[54:55]
	v_mov_b64_e32 v[8:9], v[56:57]
	v_mov_b64_e32 v[10:11], v[58:59]
	v_mov_b64_e32 v[12:13], v[60:61]
	v_mov_b64_e32 v[14:15], v[62:63]
	s_cbranch_vccnz .LBB0_832
	ds_read_b128 v[240:243], v175 offset:34816
	ds_read_b128 v[244:247], v175 offset:34848
	ds_read_b128 v[248:251], v175 offset:34880
	ds_read_b128 v[252:255], v175 offset:34912
	s_waitcnt lgkmcnt(3)
	v_mfma_f32_32x32x16_bf16 v[48:63], v[240:243], v[84:87], 0
	ds_read_b128 v[240:243], v175 offset:39424
	s_waitcnt lgkmcnt(3)
	v_mfma_f32_32x32x16_bf16 v[48:63], v[244:247], v[92:95], v[48:63]
	ds_read_b128 v[244:247], v175 offset:39456
	s_waitcnt lgkmcnt(3)
	v_mfma_f32_32x32x16_bf16 v[48:63], v[248:251], v[80:83], v[48:63]
	ds_read_b128 v[248:251], v175 offset:39488
	s_waitcnt lgkmcnt(3)
	v_mfma_f32_32x32x16_bf16 v[48:63], v[252:255], v[88:91], v[48:63]
	ds_read_b128 v[252:255], v175 offset:39520
	s_waitcnt lgkmcnt(3)
	v_mfma_f32_32x32x16_bf16 v[32:47], v[240:243], v[84:87], 0
	ds_read_b128 v[240:243], v175 offset:44032
	s_waitcnt lgkmcnt(3)
	v_mfma_f32_32x32x16_bf16 v[32:47], v[244:247], v[92:95], v[32:47]
	ds_read_b128 v[244:247], v175 offset:44064
	s_waitcnt lgkmcnt(3)
	v_mfma_f32_32x32x16_bf16 v[32:47], v[248:251], v[80:83], v[32:47]
	ds_read_b128 v[248:251], v175 offset:44096
	s_waitcnt lgkmcnt(3)
	v_mfma_f32_32x32x16_bf16 v[32:47], v[252:255], v[88:91], v[32:47]
	ds_read_b128 v[252:255], v175 offset:44128
	s_waitcnt lgkmcnt(3)
	v_mfma_f32_32x32x16_bf16 v[16:31], v[240:243], v[84:87], 0
	ds_read_b128 v[240:243], v175 offset:48640
	s_waitcnt lgkmcnt(3)
	v_mfma_f32_32x32x16_bf16 v[16:31], v[244:247], v[92:95], v[16:31]
	ds_read_b128 v[244:247], v175 offset:48672
	s_waitcnt lgkmcnt(3)
	v_mfma_f32_32x32x16_bf16 v[16:31], v[248:251], v[80:83], v[16:31]
	ds_read_b128 v[248:251], v175 offset:48704
	s_waitcnt lgkmcnt(3)
	v_mfma_f32_32x32x16_bf16 v[16:31], v[252:255], v[88:91], v[16:31]
	ds_read_b128 v[252:255], v175 offset:48736
	s_waitcnt lgkmcnt(3)
	v_mfma_f32_32x32x16_bf16 v[0:15], v[240:243], v[84:87], 0
	s_waitcnt lgkmcnt(2)
	v_mfma_f32_32x32x16_bf16 v[0:15], v[244:247], v[92:95], v[0:15]
	s_waitcnt lgkmcnt(1)
	v_mfma_f32_32x32x16_bf16 v[0:15], v[248:251], v[80:83], v[0:15]
	s_waitcnt lgkmcnt(0)
	v_mfma_f32_32x32x16_bf16 v[0:15], v[252:255], v[88:91], v[0:15]
	s_nop 7
.LBB0_832:
	v_add_u32_e32 v130, 0x8800, v130
	s_waitcnt lgkmcnt(0)
	s_barrier
	s_barrier
	s_waitcnt vmcnt(0)
	ds_write_b128 v177, v[76:79]
	v_add_u32_e32 v76, v130, v131
	v_mad_i64_i32 v[134:135], s[6:7], v128, s79, 0
	v_mad_i64_i32 v[128:129], s[6:7], v129, s79, 0
	v_add_u32_e32 v76, 0x9000, v76
	ds_write2_b64 v76, v[68:69], v[70:71] offset1:2
	ds_write_b128 v180, v[72:75]
	v_add_u32_e32 v68, v130, v132
	s_add_u32 s6, s20, 0x186000
	v_add_u32_e32 v68, 0x9000, v68
	s_addc_u32 s7, s21, 0
	ds_write2_b64 v68, v[64:65], v[66:67] offset1:2
	v_lshl_add_u64 v[64:65], s[6:7], 0, v[134:135]
	v_lshl_add_u64 v[64:65], v[96:97], 1, v[64:65]
	v_lshl_add_u64 v[66:67], s[6:7], 0, v[128:129]
	v_lshl_add_u64 v[66:67], v[100:101], 1, v[66:67]
	global_load_dwordx4 v[140:143], v[64:65], off
	global_load_dwordx4 v[132:135], v[66:67], off
	global_load_dwordx4 v[136:139], v[98:99], off offset:384
	global_load_dwordx4 v[128:131], v[102:103], off offset:384
	s_and_b64 vcc, exec, s[2:3]
	s_cbranch_vccz .LBB0_834
	ds_read_b128 v[240:243], v175 offset:34816
	ds_read_b128 v[244:247], v175 offset:34848
	ds_read_b128 v[248:251], v175 offset:34880
	ds_read_b128 v[252:255], v175 offset:34912
	s_waitcnt lgkmcnt(3)
	v_mfma_f32_32x32x16_bf16 v[48:63], v[240:243], v[84:87], v[48:63]
	ds_read_b128 v[240:243], v175 offset:39424
	s_waitcnt lgkmcnt(3)
	v_mfma_f32_32x32x16_bf16 v[48:63], v[244:247], v[92:95], v[48:63]
	ds_read_b128 v[244:247], v175 offset:39456
	s_waitcnt lgkmcnt(3)
	v_mfma_f32_32x32x16_bf16 v[48:63], v[248:251], v[80:83], v[48:63]
	ds_read_b128 v[248:251], v175 offset:39488
	s_waitcnt lgkmcnt(3)
	v_mfma_f32_32x32x16_bf16 v[48:63], v[252:255], v[88:91], v[48:63]
	ds_read_b128 v[252:255], v175 offset:39520
	s_waitcnt lgkmcnt(3)
	v_mfma_f32_32x32x16_bf16 v[32:47], v[240:243], v[84:87], v[32:47]
	ds_read_b128 v[240:243], v175 offset:44032
	s_waitcnt lgkmcnt(3)
	v_mfma_f32_32x32x16_bf16 v[32:47], v[244:247], v[92:95], v[32:47]
	ds_read_b128 v[244:247], v175 offset:44064
	s_waitcnt lgkmcnt(3)
	v_mfma_f32_32x32x16_bf16 v[32:47], v[248:251], v[80:83], v[32:47]
	ds_read_b128 v[248:251], v175 offset:44096
	s_waitcnt lgkmcnt(3)
	v_mfma_f32_32x32x16_bf16 v[32:47], v[252:255], v[88:91], v[32:47]
	ds_read_b128 v[252:255], v175 offset:44128
	s_waitcnt lgkmcnt(3)
	v_mfma_f32_32x32x16_bf16 v[16:31], v[240:243], v[84:87], v[16:31]
	ds_read_b128 v[240:243], v175 offset:48640
	s_waitcnt lgkmcnt(3)
	v_mfma_f32_32x32x16_bf16 v[16:31], v[244:247], v[92:95], v[16:31]
	ds_read_b128 v[244:247], v175 offset:48672
	s_waitcnt lgkmcnt(3)
	v_mfma_f32_32x32x16_bf16 v[16:31], v[248:251], v[80:83], v[16:31]
	ds_read_b128 v[248:251], v175 offset:48704
	s_waitcnt lgkmcnt(3)
	v_mfma_f32_32x32x16_bf16 v[16:31], v[252:255], v[88:91], v[16:31]
	ds_read_b128 v[252:255], v175 offset:48736
	s_waitcnt lgkmcnt(3)
	v_mfma_f32_32x32x16_bf16 v[0:15], v[240:243], v[84:87], v[0:15]
	s_waitcnt lgkmcnt(2)
	v_mfma_f32_32x32x16_bf16 v[0:15], v[244:247], v[92:95], v[0:15]
	s_waitcnt lgkmcnt(1)
	v_mfma_f32_32x32x16_bf16 v[0:15], v[248:251], v[80:83], v[0:15]
	s_waitcnt lgkmcnt(0)
	v_mfma_f32_32x32x16_bf16 v[0:15], v[252:255], v[88:91], v[0:15]
	s_nop 7

.LBB0_836:
	v_exp_f32_e32 v150, v80
	v_exp_f32_e32 v151, v81
	v_exp_f32_e32 v96, v96
	v_exp_f32_e32 v97, v97
	v_exp_f32_e32 v82, v82
	v_exp_f32_e32 v83, v83
	v_exp_f32_e32 v98, v98
	v_exp_f32_e32 v99, v99
	v_exp_f32_e32 v84, v84
	v_exp_f32_e32 v85, v85
	v_exp_f32_e32 v100, v100
	v_exp_f32_e32 v101, v101
	v_exp_f32_e32 v86, v86
	v_exp_f32_e32 v87, v87
	v_exp_f32_e32 v102, v102
	v_exp_f32_e32 v103, v103
	v_exp_f32_e32 v88, v88
	v_exp_f32_e32 v89, v89
	v_exp_f32_e32 v104, v104
	v_exp_f32_e32 v105, v105
	v_exp_f32_e32 v90, v90
	v_exp_f32_e32 v91, v91
	v_exp_f32_e32 v106, v106
	v_exp_f32_e32 v107, v107
	v_exp_f32_e32 v92, v92
	v_exp_f32_e32 v93, v93
	v_exp_f32_e32 v108, v108
	v_exp_f32_e32 v109, v109
	v_exp_f32_e32 v94, v94
	v_exp_f32_e32 v95, v95
	v_exp_f32_e32 v110, v110
	v_exp_f32_e32 v111, v111
	v_cndmask_b32_e64 v65, 0, 1, s[4:5]
	v_add_u32_e32 v152, 0x8800, v175
	v_cvt_pk_bf16_f32 v70, v150, v151
	v_cvt_pk_bf16_f32 v71, v82, v83
	v_cvt_pk_bf16_f32 v72, v84, v85
	v_cvt_pk_bf16_f32 v73, v86, v87
	v_cvt_pk_bf16_f32 v66, v96, v97
	v_cvt_pk_bf16_f32 v67, v98, v99
	v_cvt_pk_bf16_f32 v68, v100, v101
	v_cvt_pk_bf16_f32 v69, v102, v103
	v_cvt_pk_bf16_f32 v78, v88, v89
	v_cvt_pk_bf16_f32 v79, v90, v91
	v_cvt_pk_bf16_f32 v80, v92, v93
	v_cvt_pk_bf16_f32 v81, v94, v95
	v_cvt_pk_bf16_f32 v74, v104, v105
	v_cvt_pk_bf16_f32 v75, v106, v107
	v_cvt_pk_bf16_f32 v76, v108, v109
	v_cmp_ne_u32_e64 s[6:7], 1, v65
	s_andn2_b64 vcc, exec, s[4:5]
	v_cvt_pk_bf16_f32 v77, v110, v111
	s_cbranch_vccnz .LBB0_838
	ds_read_b128 v[240:243], v175 offset:53248
	ds_read_b128 v[244:247], v175 offset:53280
	ds_read_b128 v[248:251], v175 offset:53312
	ds_read_b128 v[252:255], v175 offset:53344
	s_waitcnt lgkmcnt(3)
	v_mfma_f32_32x32x16_bf16 v[48:63], v[240:243], v[70:73], v[48:63]
	ds_read_b128 v[240:243], v175 offset:57856
	s_waitcnt lgkmcnt(3)
	v_mfma_f32_32x32x16_bf16 v[48:63], v[244:247], v[78:81], v[48:63]
	ds_read_b128 v[244:247], v175 offset:57888
	s_waitcnt lgkmcnt(3)
	v_mfma_f32_32x32x16_bf16 v[48:63], v[248:251], v[66:69], v[48:63]
	ds_read_b128 v[248:251], v175 offset:57920
	s_waitcnt lgkmcnt(3)
	v_mfma_f32_32x32x16_bf16 v[48:63], v[252:255], v[74:77], v[48:63]
	ds_read_b128 v[252:255], v175 offset:57952
	s_waitcnt lgkmcnt(3)
	v_mfma_f32_32x32x16_bf16 v[32:47], v[240:243], v[70:73], v[32:47]
	ds_read_b128 v[240:243], v175 offset:62464
	s_waitcnt lgkmcnt(3)
	v_mfma_f32_32x32x16_bf16 v[32:47], v[244:247], v[78:81], v[32:47]
	ds_read_b128 v[244:247], v175 offset:62496
	s_waitcnt lgkmcnt(3)
	v_mfma_f32_32x32x16_bf16 v[32:47], v[248:251], v[66:69], v[32:47]
	ds_read_b128 v[248:251], v175 offset:62528
	s_waitcnt lgkmcnt(3)
	v_mfma_f32_32x32x16_bf16 v[32:47], v[252:255], v[74:77], v[32:47]
	ds_read_b128 v[252:255], v175 offset:62560
	s_waitcnt lgkmcnt(3)
	v_mfma_f32_32x32x16_bf16 v[16:31], v[240:243], v[70:73], v[16:31]
	ds_read_b128 v[240:243], v152 offset:32256
	s_waitcnt lgkmcnt(3)
	v_mfma_f32_32x32x16_bf16 v[16:31], v[244:247], v[78:81], v[16:31]
	ds_read_b128 v[244:247], v152 offset:32288
	s_waitcnt lgkmcnt(3)
	v_mfma_f32_32x32x16_bf16 v[16:31], v[248:251], v[66:69], v[16:31]
	ds_read_b128 v[248:251], v152 offset:32320
	s_waitcnt lgkmcnt(3)
	v_mfma_f32_32x32x16_bf16 v[16:31], v[252:255], v[74:77], v[16:31]
	ds_read_b128 v[252:255], v152 offset:32352
	s_waitcnt lgkmcnt(3)
	v_mfma_f32_32x32x16_bf16 v[0:15], v[240:243], v[70:73], v[0:15]
	s_waitcnt lgkmcnt(2)
	v_mfma_f32_32x32x16_bf16 v[0:15], v[244:247], v[78:81], v[0:15]
	s_waitcnt lgkmcnt(1)
	v_mfma_f32_32x32x16_bf16 v[0:15], v[248:251], v[66:69], v[0:15]
	s_waitcnt lgkmcnt(0)
	v_mfma_f32_32x32x16_bf16 v[0:15], v[252:255], v[74:77], v[0:15]
	s_nop 7
.LBB0_838:
	s_waitcnt lgkmcnt(0)
	s_barrier
	s_barrier
	s_movk_i32 s5, 0x1000
	s_andn2_b64 vcc, exec, s[2:3]
	s_waitcnt vmcnt(0)
	ds_write_b128 v177, v[140:143] offset:17408
	ds_write2_b64 v178, v[136:137], v[138:139] offset1:2
	ds_write_b128 v180, v[132:135] offset:17408
	ds_write2_b64 v179, v[128:129], v[130:131] offset1:2
	s_cbranch_vccnz .LBB0_840
	ds_read_b128 v[240:243], v175 offset:53248
	ds_read_b128 v[244:247], v175 offset:53280
	ds_read_b128 v[248:251], v175 offset:53312
	ds_read_b128 v[252:255], v175 offset:53344
	s_waitcnt lgkmcnt(3)
	v_mfma_f32_32x32x16_bf16 v[48:63], v[240:243], v[70:73], v[48:63]
	ds_read_b128 v[240:243], v175 offset:57856
	s_waitcnt lgkmcnt(3)
	v_mfma_f32_32x32x16_bf16 v[48:63], v[244:247], v[78:81], v[48:63]
	ds_read_b128 v[244:247], v175 offset:57888
	s_waitcnt lgkmcnt(3)
	v_mfma_f32_32x32x16_bf16 v[48:63], v[248:251], v[66:69], v[48:63]
	ds_read_b128 v[248:251], v175 offset:57920
	s_waitcnt lgkmcnt(3)
	v_mfma_f32_32x32x16_bf16 v[48:63], v[252:255], v[74:77], v[48:63]
	ds_read_b128 v[252:255], v175 offset:57952
	s_waitcnt lgkmcnt(3)
	v_mfma_f32_32x32x16_bf16 v[32:47], v[240:243], v[70:73], v[32:47]
	ds_read_b128 v[240:243], v175 offset:62464
	s_waitcnt lgkmcnt(3)
	v_mfma_f32_32x32x16_bf16 v[32:47], v[244:247], v[78:81], v[32:47]
	ds_read_b128 v[244:247], v175 offset:62496
	s_waitcnt lgkmcnt(3)
	v_mfma_f32_32x32x16_bf16 v[32:47], v[248:251], v[66:69], v[32:47]
	ds_read_b128 v[248:251], v175 offset:62528
	s_waitcnt lgkmcnt(3)
	v_mfma_f32_32x32x16_bf16 v[32:47], v[252:255], v[74:77], v[32:47]
	ds_read_b128 v[252:255], v175 offset:62560
	s_waitcnt lgkmcnt(3)
	v_mfma_f32_32x32x16_bf16 v[16:31], v[240:243], v[70:73], v[16:31]
	ds_read_b128 v[240:243], v152 offset:32256
	s_waitcnt lgkmcnt(3)
	v_mfma_f32_32x32x16_bf16 v[16:31], v[244:247], v[78:81], v[16:31]
	ds_read_b128 v[244:247], v152 offset:32288
	s_waitcnt lgkmcnt(3)
	v_mfma_f32_32x32x16_bf16 v[16:31], v[248:251], v[66:69], v[16:31]
	ds_read_b128 v[248:251], v152 offset:32320
	s_waitcnt lgkmcnt(3)
	v_mfma_f32_32x32x16_bf16 v[16:31], v[252:255], v[74:77], v[16:31]
	ds_read_b128 v[252:255], v152 offset:32352
	s_waitcnt lgkmcnt(3)
	v_mfma_f32_32x32x16_bf16 v[0:15], v[240:243], v[70:73], v[0:15]
	s_waitcnt lgkmcnt(2)
	v_mfma_f32_32x32x16_bf16 v[0:15], v[244:247], v[78:81], v[0:15]
	s_waitcnt lgkmcnt(1)
	v_mfma_f32_32x32x16_bf16 v[0:15], v[248:251], v[66:69], v[0:15]
	s_waitcnt lgkmcnt(0)
	v_mfma_f32_32x32x16_bf16 v[0:15], v[252:255], v[74:77], v[0:15]
	s_nop 7

.LBB0_842:
	v_exp_f32_e32 v96, v96
	v_exp_f32_e32 v97, v97
	v_exp_f32_e32 v128, v80
	v_exp_f32_e32 v129, v81
	v_exp_f32_e32 v98, v98
	v_exp_f32_e32 v99, v99
	v_exp_f32_e32 v130, v82
	v_exp_f32_e32 v131, v83
	v_exp_f32_e32 v100, v100
	v_exp_f32_e32 v101, v101
	v_exp_f32_e32 v132, v84
	v_exp_f32_e32 v133, v85
	v_exp_f32_e32 v102, v102
	v_exp_f32_e32 v103, v103
	v_exp_f32_e32 v134, v86
	v_exp_f32_e32 v135, v87
	v_exp_f32_e32 v104, v104
	v_exp_f32_e32 v105, v105
	v_exp_f32_e32 v136, v88
	v_exp_f32_e32 v137, v89
	v_exp_f32_e32 v106, v106
	v_exp_f32_e32 v107, v107
	v_exp_f32_e32 v138, v90
	v_exp_f32_e32 v139, v91
	v_exp_f32_e32 v108, v108
	v_exp_f32_e32 v109, v109
	v_exp_f32_e32 v140, v92
	v_exp_f32_e32 v141, v93
	v_exp_f32_e32 v110, v110
	v_exp_f32_e32 v111, v111
	v_exp_f32_e32 v142, v94
	v_exp_f32_e32 v143, v95
	v_cvt_pk_bf16_f32 v84, v96, v97
	v_cvt_pk_bf16_f32 v85, v98, v99
	v_cvt_pk_bf16_f32 v86, v100, v101
	v_cvt_pk_bf16_f32 v87, v102, v103
	v_cvt_pk_bf16_f32 v80, v128, v129
	v_cvt_pk_bf16_f32 v81, v130, v131
	v_cvt_pk_bf16_f32 v82, v132, v133
	v_cvt_pk_bf16_f32 v83, v134, v135
	v_cvt_pk_bf16_f32 v92, v104, v105
	v_cvt_pk_bf16_f32 v93, v106, v107
	v_cvt_pk_bf16_f32 v94, v108, v109
	v_cvt_pk_bf16_f32 v95, v110, v111
	v_cvt_pk_bf16_f32 v88, v136, v137
	v_cvt_pk_bf16_f32 v89, v138, v139
	v_cvt_pk_bf16_f32 v90, v140, v141
	s_and_b64 vcc, exec, s[6:7]
	v_cvt_pk_bf16_f32 v91, v142, v143
	s_cbranch_vccnz .LBB0_844
	ds_read_b128 v[240:243], v152 offset:36864
	ds_read_b128 v[244:247], v152 offset:36896
	ds_read_b128 v[248:251], v152 offset:36928
	ds_read_b128 v[252:255], v152 offset:36960
	s_waitcnt lgkmcnt(3)
	v_mfma_f32_32x32x16_bf16 v[48:63], v[240:243], v[84:87], v[48:63]
	ds_read_b128 v[240:243], v152 offset:41472
	s_waitcnt lgkmcnt(3)
	v_mfma_f32_32x32x16_bf16 v[48:63], v[244:247], v[92:95], v[48:63]
	ds_read_b128 v[244:247], v152 offset:41504
	s_waitcnt lgkmcnt(3)
	v_mfma_f32_32x32x16_bf16 v[48:63], v[248:251], v[80:83], v[48:63]
	ds_read_b128 v[248:251], v152 offset:41536
	s_waitcnt lgkmcnt(3)
	v_mfma_f32_32x32x16_bf16 v[48:63], v[252:255], v[88:91], v[48:63]
	ds_read_b128 v[252:255], v152 offset:41568
	s_waitcnt lgkmcnt(3)
	v_mfma_f32_32x32x16_bf16 v[32:47], v[240:243], v[84:87], v[32:47]
	ds_read_b128 v[240:243], v152 offset:46080
	s_waitcnt lgkmcnt(3)
	v_mfma_f32_32x32x16_bf16 v[32:47], v[244:247], v[92:95], v[32:47]
	ds_read_b128 v[244:247], v152 offset:46112
	s_waitcnt lgkmcnt(3)
	v_mfma_f32_32x32x16_bf16 v[32:47], v[248:251], v[80:83], v[32:47]
	ds_read_b128 v[248:251], v152 offset:46144
	s_waitcnt lgkmcnt(3)
	v_mfma_f32_32x32x16_bf16 v[32:47], v[252:255], v[88:91], v[32:47]
	ds_read_b128 v[252:255], v152 offset:46176
	s_waitcnt lgkmcnt(3)
	v_mfma_f32_32x32x16_bf16 v[16:31], v[240:243], v[84:87], v[16:31]
	ds_read_b128 v[240:243], v152 offset:50688
	s_waitcnt lgkmcnt(3)
	v_mfma_f32_32x32x16_bf16 v[16:31], v[244:247], v[92:95], v[16:31]
	ds_read_b128 v[244:247], v152 offset:50720
	s_waitcnt lgkmcnt(3)
	v_mfma_f32_32x32x16_bf16 v[16:31], v[248:251], v[80:83], v[16:31]
	ds_read_b128 v[248:251], v152 offset:50752
	s_waitcnt lgkmcnt(3)
	v_mfma_f32_32x32x16_bf16 v[16:31], v[252:255], v[88:91], v[16:31]
	ds_read_b128 v[252:255], v152 offset:50784
	s_waitcnt lgkmcnt(3)
	v_mfma_f32_32x32x16_bf16 v[0:15], v[240:243], v[84:87], v[0:15]
	s_waitcnt lgkmcnt(2)
	v_mfma_f32_32x32x16_bf16 v[0:15], v[244:247], v[92:95], v[0:15]
	s_waitcnt lgkmcnt(1)
	v_mfma_f32_32x32x16_bf16 v[0:15], v[248:251], v[80:83], v[0:15]
	s_waitcnt lgkmcnt(0)
	v_mfma_f32_32x32x16_bf16 v[0:15], v[252:255], v[88:91], v[0:15]
	s_nop 7
.LBB0_844:
	s_waitcnt lgkmcnt(0)
	s_barrier
	s_barrier
	s_and_b64 vcc, exec, s[2:3]
	s_cbranch_vccz .LBB0_846
	ds_read_b128 v[240:243], v152 offset:36864
	ds_read_b128 v[244:247], v152 offset:36896
	ds_read_b128 v[248:251], v152 offset:36928
	ds_read_b128 v[252:255], v152 offset:36960
	s_waitcnt lgkmcnt(3)
	v_mfma_f32_32x32x16_bf16 v[48:63], v[240:243], v[84:87], v[48:63]
	ds_read_b128 v[240:243], v152 offset:41472
	s_waitcnt lgkmcnt(3)
	v_mfma_f32_32x32x16_bf16 v[48:63], v[244:247], v[92:95], v[48:63]
	ds_read_b128 v[244:247], v152 offset:41504
	s_waitcnt lgkmcnt(3)
	v_mfma_f32_32x32x16_bf16 v[48:63], v[248:251], v[80:83], v[48:63]
	ds_read_b128 v[248:251], v152 offset:41536
	s_waitcnt lgkmcnt(3)
	v_mfma_f32_32x32x16_bf16 v[48:63], v[252:255], v[88:91], v[48:63]
	ds_read_b128 v[252:255], v152 offset:41568
	s_waitcnt lgkmcnt(3)
	v_mfma_f32_32x32x16_bf16 v[32:47], v[240:243], v[84:87], v[32:47]
	ds_read_b128 v[240:243], v152 offset:46080
	s_waitcnt lgkmcnt(3)
	v_mfma_f32_32x32x16_bf16 v[32:47], v[244:247], v[92:95], v[32:47]
	ds_read_b128 v[244:247], v152 offset:46112
	s_waitcnt lgkmcnt(3)
	v_mfma_f32_32x32x16_bf16 v[32:47], v[248:251], v[80:83], v[32:47]
	ds_read_b128 v[248:251], v152 offset:46144
	s_waitcnt lgkmcnt(3)
	v_mfma_f32_32x32x16_bf16 v[32:47], v[252:255], v[88:91], v[32:47]
	ds_read_b128 v[252:255], v152 offset:46176
	s_waitcnt lgkmcnt(3)
	v_mfma_f32_32x32x16_bf16 v[16:31], v[240:243], v[84:87], v[16:31]
	ds_read_b128 v[240:243], v152 offset:50688
	s_waitcnt lgkmcnt(3)
	v_mfma_f32_32x32x16_bf16 v[16:31], v[244:247], v[92:95], v[16:31]
	ds_read_b128 v[244:247], v152 offset:50720
	s_waitcnt lgkmcnt(3)
	v_mfma_f32_32x32x16_bf16 v[16:31], v[248:251], v[80:83], v[16:31]
	ds_read_b128 v[248:251], v152 offset:50752
	s_waitcnt lgkmcnt(3)
	v_mfma_f32_32x32x16_bf16 v[16:31], v[252:255], v[88:91], v[16:31]
	ds_read_b128 v[252:255], v152 offset:50784
	s_waitcnt lgkmcnt(3)
	v_mfma_f32_32x32x16_bf16 v[0:15], v[240:243], v[84:87], v[0:15]
	s_waitcnt lgkmcnt(2)
	v_mfma_f32_32x32x16_bf16 v[0:15], v[244:247], v[92:95], v[0:15]
	s_waitcnt lgkmcnt(1)
	v_mfma_f32_32x32x16_bf16 v[0:15], v[248:251], v[80:83], v[0:15]
	s_waitcnt lgkmcnt(0)
	v_mfma_f32_32x32x16_bf16 v[0:15], v[252:255], v[88:91], v[0:15]
	s_nop 7

.LBB0_848:
	v_exp_f32_e32 v80, v80
	v_exp_f32_e32 v81, v81
	v_exp_f32_e32 v96, v64
	v_exp_f32_e32 v97, v65
	v_exp_f32_e32 v82, v82
	v_exp_f32_e32 v83, v83
	v_exp_f32_e32 v98, v66
	v_exp_f32_e32 v99, v67
	v_exp_f32_e32 v84, v84
	v_exp_f32_e32 v85, v85
	v_exp_f32_e32 v100, v68
	v_exp_f32_e32 v101, v69
	v_exp_f32_e32 v86, v86
	v_exp_f32_e32 v87, v87
	v_exp_f32_e32 v102, v70
	v_exp_f32_e32 v103, v71
	v_exp_f32_e32 v88, v88
	v_exp_f32_e32 v89, v89
	v_exp_f32_e32 v104, v72
	v_exp_f32_e32 v105, v73
	v_exp_f32_e32 v90, v90
	v_exp_f32_e32 v91, v91
	v_exp_f32_e32 v106, v74
	v_exp_f32_e32 v107, v75
	v_exp_f32_e32 v92, v92
	v_exp_f32_e32 v93, v93
	v_exp_f32_e32 v108, v76
	v_exp_f32_e32 v109, v77
	v_exp_f32_e32 v94, v94
	v_exp_f32_e32 v95, v95
	v_exp_f32_e32 v110, v78
	v_exp_f32_e32 v111, v79
	v_cvt_pk_bf16_f32 v68, v80, v81
	v_cvt_pk_bf16_f32 v69, v82, v83
	v_cvt_pk_bf16_f32 v70, v84, v85
	v_cvt_pk_bf16_f32 v71, v86, v87
	v_cvt_pk_bf16_f32 v64, v96, v97
	v_cvt_pk_bf16_f32 v65, v98, v99
	v_cvt_pk_bf16_f32 v66, v100, v101
	v_cvt_pk_bf16_f32 v67, v102, v103
	v_cvt_pk_bf16_f32 v76, v88, v89
	v_cvt_pk_bf16_f32 v77, v90, v91
	v_cvt_pk_bf16_f32 v78, v92, v93
	v_cvt_pk_bf16_f32 v79, v94, v95
	v_cvt_pk_bf16_f32 v72, v104, v105
	v_cvt_pk_bf16_f32 v73, v106, v107
	v_cvt_pk_bf16_f32 v74, v108, v109
	s_and_b64 vcc, exec, s[6:7]
	v_cvt_pk_bf16_f32 v75, v110, v111
	s_cbranch_vccnz .LBB0_850
	ds_read_b128 v[240:243], v175 offset:34816
	ds_read_b128 v[244:247], v175 offset:34848
	ds_read_b128 v[248:251], v175 offset:34880
	ds_read_b128 v[252:255], v175 offset:34912
	s_waitcnt lgkmcnt(3)
	v_mfma_f32_32x32x16_bf16 v[48:63], v[240:243], v[68:71], v[48:63]
	ds_read_b128 v[240:243], v175 offset:39424
	s_waitcnt lgkmcnt(3)
	v_mfma_f32_32x32x16_bf16 v[48:63], v[244:247], v[76:79], v[48:63]
	ds_read_b128 v[244:247], v175 offset:39456
	s_waitcnt lgkmcnt(3)
	v_mfma_f32_32x32x16_bf16 v[48:63], v[248:251], v[64:67], v[48:63]
	ds_read_b128 v[248:251], v175 offset:39488
	s_waitcnt lgkmcnt(3)
	v_mfma_f32_32x32x16_bf16 v[48:63], v[252:255], v[72:75], v[48:63]
	ds_read_b128 v[252:255], v175 offset:39520
	s_waitcnt lgkmcnt(3)
	v_mfma_f32_32x32x16_bf16 v[32:47], v[240:243], v[68:71], v[32:47]
	ds_read_b128 v[240:243], v175 offset:44032
	s_waitcnt lgkmcnt(3)
	v_mfma_f32_32x32x16_bf16 v[32:47], v[244:247], v[76:79], v[32:47]
	ds_read_b128 v[244:247], v175 offset:44064
	s_waitcnt lgkmcnt(3)
	v_mfma_f32_32x32x16_bf16 v[32:47], v[248:251], v[64:67], v[32:47]
	ds_read_b128 v[248:251], v175 offset:44096
	s_waitcnt lgkmcnt(3)
	v_mfma_f32_32x32x16_bf16 v[32:47], v[252:255], v[72:75], v[32:47]
	ds_read_b128 v[252:255], v175 offset:44128
	s_waitcnt lgkmcnt(3)
	v_mfma_f32_32x32x16_bf16 v[16:31], v[240:243], v[68:71], v[16:31]
	ds_read_b128 v[240:243], v175 offset:48640
	s_waitcnt lgkmcnt(3)
	v_mfma_f32_32x32x16_bf16 v[16:31], v[244:247], v[76:79], v[16:31]
	ds_read_b128 v[244:247], v175 offset:48672
	s_waitcnt lgkmcnt(3)
	v_mfma_f32_32x32x16_bf16 v[16:31], v[248:251], v[64:67], v[16:31]
	ds_read_b128 v[248:251], v175 offset:48704
	s_waitcnt lgkmcnt(3)
	v_mfma_f32_32x32x16_bf16 v[16:31], v[252:255], v[72:75], v[16:31]
	ds_read_b128 v[252:255], v175 offset:48736
	s_waitcnt lgkmcnt(3)
	v_mfma_f32_32x32x16_bf16 v[0:15], v[240:243], v[68:71], v[0:15]
	s_waitcnt lgkmcnt(2)
	v_mfma_f32_32x32x16_bf16 v[0:15], v[244:247], v[76:79], v[0:15]
	s_waitcnt lgkmcnt(1)
	v_mfma_f32_32x32x16_bf16 v[0:15], v[248:251], v[64:67], v[0:15]
	s_waitcnt lgkmcnt(0)
	v_mfma_f32_32x32x16_bf16 v[0:15], v[252:255], v[72:75], v[0:15]
	s_nop 7
.LBB0_850:
	s_waitcnt lgkmcnt(0)
	s_barrier
	s_barrier
	s_and_b64 vcc, exec, s[2:3]
	s_cbranch_vccz .LBB0_852
	ds_read_b128 v[240:243], v175 offset:34816
	ds_read_b128 v[244:247], v175 offset:34848
	ds_read_b128 v[248:251], v175 offset:34880
	ds_read_b128 v[252:255], v175 offset:34912
	s_waitcnt lgkmcnt(3)
	v_mfma_f32_32x32x16_bf16 v[48:63], v[240:243], v[68:71], v[48:63]
	ds_read_b128 v[240:243], v175 offset:39424
	s_waitcnt lgkmcnt(3)
	v_mfma_f32_32x32x16_bf16 v[48:63], v[244:247], v[76:79], v[48:63]
	ds_read_b128 v[244:247], v175 offset:39456
	s_waitcnt lgkmcnt(3)
	v_mfma_f32_32x32x16_bf16 v[48:63], v[248:251], v[64:67], v[48:63]
	ds_read_b128 v[248:251], v175 offset:39488
	s_waitcnt lgkmcnt(3)
	v_mfma_f32_32x32x16_bf16 v[48:63], v[252:255], v[72:75], v[48:63]
	ds_read_b128 v[252:255], v175 offset:39520
	s_waitcnt lgkmcnt(3)
	v_mfma_f32_32x32x16_bf16 v[32:47], v[240:243], v[68:71], v[32:47]
	ds_read_b128 v[240:243], v175 offset:44032
	s_waitcnt lgkmcnt(3)
	v_mfma_f32_32x32x16_bf16 v[32:47], v[244:247], v[76:79], v[32:47]
	ds_read_b128 v[244:247], v175 offset:44064
	s_waitcnt lgkmcnt(3)
	v_mfma_f32_32x32x16_bf16 v[32:47], v[248:251], v[64:67], v[32:47]
	ds_read_b128 v[248:251], v175 offset:44096
	s_waitcnt lgkmcnt(3)
	v_mfma_f32_32x32x16_bf16 v[32:47], v[252:255], v[72:75], v[32:47]
	ds_read_b128 v[252:255], v175 offset:44128
	s_waitcnt lgkmcnt(3)
	v_mfma_f32_32x32x16_bf16 v[16:31], v[240:243], v[68:71], v[16:31]
	ds_read_b128 v[240:243], v175 offset:48640
	s_waitcnt lgkmcnt(3)
	v_mfma_f32_32x32x16_bf16 v[16:31], v[244:247], v[76:79], v[16:31]
	ds_read_b128 v[244:247], v175 offset:48672
	s_waitcnt lgkmcnt(3)
	v_mfma_f32_32x32x16_bf16 v[16:31], v[248:251], v[64:67], v[16:31]
	ds_read_b128 v[248:251], v175 offset:48704
	s_waitcnt lgkmcnt(3)
	v_mfma_f32_32x32x16_bf16 v[16:31], v[252:255], v[72:75], v[16:31]
	ds_read_b128 v[252:255], v175 offset:48736
	s_waitcnt lgkmcnt(3)
	v_mfma_f32_32x32x16_bf16 v[0:15], v[240:243], v[68:71], v[0:15]
	s_waitcnt lgkmcnt(2)
	v_mfma_f32_32x32x16_bf16 v[0:15], v[244:247], v[76:79], v[0:15]
	s_waitcnt lgkmcnt(1)
	v_mfma_f32_32x32x16_bf16 v[0:15], v[248:251], v[64:67], v[0:15]
	s_waitcnt lgkmcnt(0)
	v_mfma_f32_32x32x16_bf16 v[0:15], v[252:255], v[72:75], v[0:15]
	s_nop 7

.LBB0_854:
	s_cmpk_gt_u32 s10, 0xff
	s_waitcnt lgkmcnt(0)
	s_barrier
	s_barrier
	s_cbranch_scc1 .LBB0_829
	s_lshl_b32 s3, s10, 8
	v_lshl_add_u32 v68, v64, 2, 0
	s_and_b32 s4, s3, 0xc000
	v_add_u32_e32 v69, s4, v68
	ds_read2st64_b32 v[96:97], v69 offset1:1
	ds_read2st64_b32 v[98:99], v69 offset0:2 offset1:3
	ds_read2st64_b32 v[104:105], v69 offset0:4 offset1:5
	ds_read2st64_b32 v[108:109], v69 offset0:6 offset1:7
	ds_read2st64_b32 v[112:113], v69 offset0:8 offset1:9
	ds_read2st64_b32 v[114:115], v69 offset0:10 offset1:11
	ds_read2st64_b32 v[120:121], v69 offset0:12 offset1:13
	ds_read2st64_b32 v[124:125], v69 offset0:14 offset1:15
	ds_read2st64_b32 v[126:127], v69 offset0:16 offset1:17
	ds_read2st64_b32 v[122:123], v69 offset0:18 offset1:19
	ds_read2st64_b32 v[128:129], v69 offset0:20 offset1:21
	ds_read2st64_b32 v[134:135], v69 offset0:22 offset1:23
	ds_read2st64_b32 v[130:131], v69 offset0:24 offset1:25
	ds_read2st64_b32 v[138:139], v69 offset0:26 offset1:27
	ds_read2st64_b32 v[142:143], v69 offset0:28 offset1:29
	ds_read2st64_b32 v[166:167], v69 offset0:30 offset1:31
	ds_read2st64_b32 v[136:137], v69 offset0:32 offset1:33
	ds_read2st64_b32 v[148:149], v69 offset0:34 offset1:35
	ds_read2st64_b32 v[150:151], v69 offset0:36 offset1:37
	ds_read2st64_b32 v[152:153], v69 offset0:38 offset1:39
	ds_read2st64_b32 v[102:103], v69 offset0:40 offset1:41
	ds_read2st64_b32 v[106:107], v69 offset0:42 offset1:43
	ds_read2st64_b32 v[90:91], v69 offset0:44 offset1:45
	ds_read2st64_b32 v[92:93], v69 offset0:46 offset1:47
	ds_read2st64_b32 v[86:87], v69 offset0:48 offset1:49
	ds_read2st64_b32 v[88:89], v69 offset0:50 offset1:51
	ds_read2st64_b32 v[82:83], v69 offset0:52 offset1:53
	ds_read2st64_b32 v[84:85], v69 offset0:54 offset1:55
	ds_read2st64_b32 v[78:79], v69 offset0:56 offset1:57
	ds_read2st64_b32 v[80:81], v69 offset0:58 offset1:59
	ds_read2st64_b32 v[64:65], v69 offset0:60 offset1:61
	s_or_b32 s3, s3, 0x3f00
	s_lshl_b32 s2, s17, 7
	s_movk_i32 s4, 0x1400
	s_lshl_b32 s40, s2, 1
	s_waitcnt lgkmcnt(0)
	v_pk_mul_f32 v[64:65], v[144:145], v[64:65]
	v_pk_mul_f32 v[96:97], v[144:145], v[96:97]
	v_pk_fma_f32 v[66:67], v[12:13], v[72:73], v[64:65] op_sel_hi:[1,0,1] neg_lo:[0,0,1] neg_hi:[0,0,1]
	v_add_u32_e32 v13, s3, v68
	ds_read_b32 v12, v69 offset:15872
	ds_read_b32 v13, v13
	v_pk_mul_f32 v[98:99], v[144:145], v[98:99]
	v_pk_mul_f32 v[104:105], v[144:145], v[104:105]
	v_pk_mul_f32 v[108:109], v[144:145], v[108:109]
	v_pk_mul_f32 v[112:113], v[144:145], v[112:113]
	s_waitcnt lgkmcnt(0)
	v_pk_mul_f32 v[12:13], v[144:145], v[12:13]
	v_pk_mul_f32 v[114:115], v[144:145], v[114:115]
	v_pk_fma_f32 v[64:65], v[14:15], v[72:73], v[12:13] op_sel_hi:[1,0,1] neg_lo:[0,0,1] neg_hi:[0,0,1]
	v_mov_b64_e32 v[14:15], s[14:15]
	v_mad_u64_u32 v[14:15], s[2:3], v174, s4, v[14:15]
	v_mov_b32_e32 v68, v15
	v_mad_u64_u32 v[68:69], s[2:3], v173, s4, v[68:69]
	v_mov_b32_e32 v15, v68
	v_lshrrev_b32_e32 v68, 3, v172
	v_and_b32_e32 v73, 4, v68
	v_lshl_add_u64 v[12:13], v[146:147], 0, s[40:41]
	v_lshlrev_b32_e32 v192, 1, v73
	v_lshl_add_u64 v[12:13], v[12:13], 0, v[192:193]
	s_mov_b64 s[2:3], 0x1000
	v_lshl_add_u64 v[68:69], v[12:13], 0, s[2:3]
	v_add_co_u32_e32 v12, vcc, s5, v12
	v_pk_fma_f32 v[96:97], v[48:49], v[72:73], v[96:97] op_sel_hi:[1,0,1] neg_lo:[0,0,1] neg_hi:[0,0,1]
	s_nop 0
	v_addc_co_u32_e32 v13, vcc, 0, v13, vcc
	global_load_dwordx2 v[100:101], v[12:13], off
	global_load_dwordx2 v[162:163], v[68:69], off offset:16
	global_load_dwordx2 v[140:141], v[68:69], off offset:32
	global_load_dwordx2 v[132:133], v[68:69], off offset:48
	global_load_dwordx2 v[180:181], v[68:69], off offset:64
	global_load_dwordx2 v[186:187], v[68:69], off offset:80
	global_load_dwordx2 v[184:185], v[68:69], off offset:96
	global_load_dwordx2 v[178:179], v[68:69], off offset:112
	global_load_dwordx2 v[146:147], v[68:69], off offset:128
	global_load_dwordx2 v[168:169], v[68:69], off offset:144
	global_load_dwordx2 v[160:161], v[68:69], off offset:160
	global_load_dwordx2 v[154:155], v[68:69], off offset:176
	global_load_dwordx2 v[118:119], v[68:69], off offset:192
	global_load_dwordx2 v[94:95], v[68:69], off offset:208
	global_load_dwordx2 v[70:71], v[68:69], off offset:224
	s_nop 0
	global_load_dwordx2 v[68:69], v[68:69], off offset:240
	v_lshlrev_b32_e32 v205, 2, v73
	v_pk_fma_f32 v[50:51], v[50:51], v[72:73], v[98:99] op_sel_hi:[1,0,1] neg_lo:[0,0,1] neg_hi:[0,0,1]
	v_pk_mul_f32 v[120:121], v[144:145], v[120:121]
	v_pk_mul_f32 v[124:125], v[144:145], v[124:125]
	v_pk_mul_f32 v[122:123], v[144:145], v[122:123]
	v_pk_mul_f32 v[80:81], v[144:145], v[80:81]
	v_pk_mul_f32 v[78:79], v[144:145], v[78:79]
	v_pk_mul_f32 v[116:117], v[96:97], v[96:97]
	v_lshl_add_u64 v[156:157], v[14:15], 0, s[40:41]
	global_load_dwordx4 v[12:15], v205, s[0:1]
	global_load_dwordx4 v[240:243], v205, s[0:1] offset:32
	global_load_dwordx4 v[244:247], v205, s[0:1] offset:64
	global_load_dwordx4 v[248:251], v205, s[0:1] offset:96
	v_pk_mul_f32 v[110:111], v[50:51], v[50:51]
	v_pk_mul_f32 v[74:75], v[66:67], v[66:67]
	v_pk_mul_f32 v[76:77], v[64:65], v[64:65]
	s_mov_b32 s2, 0x800000
	s_waitcnt vmcnt(0) lgkmcnt(0)
	v_lshlrev_b32_e32 v48, 16, v100
	v_mul_f32_e32 v73, 0xbfb8aa3b, v48
	v_exp_f32_e32 v73, v73
	v_and_b32_e32 v49, 0xffff0000, v100
	v_add_f32_e32 v73, 1.0, v73
	v_rcp_f32_e32 v98, v73
	v_mul_f32_e32 v73, 0xbfb8aa3b, v49
	v_exp_f32_e32 v73, v73
	s_nop 0
	v_add_f32_e32 v73, 1.0, v73
	v_rcp_f32_e32 v99, v73
	s_nop 0
	v_pk_mul_f32 v[98:99], v[98:99], v[48:49]
	v_lshlrev_b32_e32 v48, 16, v101
	v_mul_f32_e32 v73, 0xbfb8aa3b, v48
	v_exp_f32_e32 v73, v73
	v_and_b32_e32 v49, 0xffff0000, v101
	v_add_f32_e32 v73, 1.0, v73
	v_rcp_f32_e32 v100, v73
	v_mul_f32_e32 v73, 0xbfb8aa3b, v49
	v_exp_f32_e32 v73, v73
	s_nop 0
	v_add_f32_e32 v73, 1.0, v73
	v_pk_fma_f32 v[52:53], v[52:53], v[72:73], v[104:105] op_sel_hi:[1,0,1] neg_lo:[0,0,1] neg_hi:[0,0,1]
	v_lshlrev_b32_e32 v104, 16, v162
	v_rcp_f32_e32 v101, v73
	v_pk_fma_f32 v[54:55], v[54:55], v[72:73], v[108:109] op_sel_hi:[1,0,1] neg_lo:[0,0,1] neg_hi:[0,0,1]
	v_mul_f32_e32 v73, 0xbfb8aa3b, v104
	v_exp_f32_e32 v73, v73
	v_and_b32_e32 v105, 0xffff0000, v162
	v_pk_mul_f32 v[158:159], v[52:53], v[52:53]
	v_pk_mul_f32 v[100:101], v[100:101], v[48:49]
	v_add_f32_e32 v73, 1.0, v73
	v_rcp_f32_e32 v108, v73
	v_mul_f32_e32 v73, 0xbfb8aa3b, v105
	v_exp_f32_e32 v73, v73
	v_lshl_add_u64 v[48:49], v[156:157], 0, v[192:193]
	v_pk_mul_f32 v[156:157], v[54:55], v[54:55]
	v_add_f32_e32 v73, 1.0, v73
	v_rcp_f32_e32 v109, v73
	s_nop 0
	v_pk_mul_f32 v[104:105], v[108:109], v[104:105]
	v_lshlrev_b32_e32 v108, 16, v163
	v_mul_f32_e32 v73, 0xbfb8aa3b, v108
	v_exp_f32_e32 v73, v73
	v_and_b32_e32 v109, 0xffff0000, v163
	v_add_f32_e32 v73, 1.0, v73
	v_rcp_f32_e32 v162, v73
	v_mul_f32_e32 v73, 0xbfb8aa3b, v109
	v_exp_f32_e32 v73, v73
	s_nop 0
	v_add_f32_e32 v73, 1.0, v73
	v_pk_fma_f32 v[56:57], v[56:57], v[72:73], v[112:113] op_sel_hi:[1,0,1] neg_lo:[0,0,1] neg_hi:[0,0,1]
	v_lshlrev_b32_e32 v112, 16, v140
	v_rcp_f32_e32 v163, v73
	v_pk_fma_f32 v[58:59], v[58:59], v[72:73], v[114:115] op_sel_hi:[1,0,1] neg_lo:[0,0,1] neg_hi:[0,0,1]
	v_mul_f32_e32 v73, 0xbfb8aa3b, v112
	v_exp_f32_e32 v73, v73
	v_and_b32_e32 v113, 0xffff0000, v140
	v_pk_mul_f32 v[164:165], v[56:57], v[56:57]
	v_pk_mul_f32 v[108:109], v[162:163], v[108:109]
	v_add_f32_e32 v73, 1.0, v73
	v_rcp_f32_e32 v114, v73
	v_mul_f32_e32 v73, 0xbfb8aa3b, v113
	v_exp_f32_e32 v73, v73
	v_pk_mul_f32 v[162:163], v[58:59], v[58:59]
	v_add_f32_e32 v73, 1.0, v73
	v_rcp_f32_e32 v115, v73
	s_nop 0
	v_pk_mul_f32 v[112:113], v[114:115], v[112:113]
	v_lshlrev_b32_e32 v114, 16, v141
	v_mul_f32_e32 v73, 0xbfb8aa3b, v114
	v_exp_f32_e32 v73, v73
	v_and_b32_e32 v115, 0xffff0000, v141
	v_add_f32_e32 v73, 1.0, v73
	v_rcp_f32_e32 v140, v73
	v_mul_f32_e32 v73, 0xbfb8aa3b, v115
	v_exp_f32_e32 v73, v73
	s_nop 0
	v_add_f32_e32 v73, 1.0, v73
	v_pk_fma_f32 v[60:61], v[60:61], v[72:73], v[120:121] op_sel_hi:[1,0,1] neg_lo:[0,0,1] neg_hi:[0,0,1]
	v_lshlrev_b32_e32 v120, 16, v132
	v_rcp_f32_e32 v141, v73
	v_pk_fma_f32 v[62:63], v[62:63], v[72:73], v[124:125] op_sel_hi:[1,0,1] neg_lo:[0,0,1] neg_hi:[0,0,1]
	v_mul_f32_e32 v73, 0xbfb8aa3b, v120
	v_exp_f32_e32 v73, v73
	v_and_b32_e32 v121, 0xffff0000, v132
	v_pk_mul_f32 v[114:115], v[140:141], v[114:115]
	v_pk_mul_f32 v[172:173], v[60:61], v[60:61]
	v_add_f32_e32 v73, 1.0, v73
	v_rcp_f32_e32 v124, v73
	v_mul_f32_e32 v73, 0xbfb8aa3b, v121
	v_exp_f32_e32 v73, v73
	v_pk_mul_f32 v[170:171], v[62:63], v[62:63]
	v_add_f32_e32 v73, 1.0, v73
	v_rcp_f32_e32 v125, v73
	s_nop 0
	v_pk_mul_f32 v[120:121], v[124:125], v[120:121]
	v_lshlrev_b32_e32 v124, 16, v133
	v_mul_f32_e32 v73, 0xbfb8aa3b, v124
	v_exp_f32_e32 v73, v73
	v_and_b32_e32 v125, 0xffff0000, v133
	v_add_f32_e32 v73, 1.0, v73
	v_rcp_f32_e32 v132, v73
	v_mul_f32_e32 v73, 0xbfb8aa3b, v125
	v_exp_f32_e32 v73, v73
	s_nop 0
	v_add_f32_e32 v73, 1.0, v73
	v_rcp_f32_e32 v133, v73
	v_pk_fma_f32 v[122:123], v[34:35], v[72:73], v[122:123] op_sel_hi:[1,0,1] neg_lo:[0,0,1] neg_hi:[0,0,1]
	v_pk_mul_f32 v[34:35], v[144:145], v[126:127]
	v_pk_mul_f32 v[174:175], v[122:123], v[122:123]
	v_pk_mul_f32 v[124:125], v[132:133], v[124:125]
	v_pk_fma_f32 v[132:133], v[32:33], v[72:73], v[34:35] op_sel_hi:[1,0,1] neg_lo:[0,0,1] neg_hi:[0,0,1]
	v_lshlrev_b32_e32 v32, 16, v180
	v_and_b32_e32 v33, 0xffff0000, v180
	v_mul_f32_e32 v34, 0xbfb8aa3b, v32
	v_mul_f32_e32 v35, 0xbfb8aa3b, v33
	v_exp_f32_e32 v34, v34
	v_exp_f32_e32 v35, v35
	v_pk_mul_f32 v[176:177], v[132:133], v[132:133]
	v_add_f32_e32 v34, 1.0, v34
	v_add_f32_e32 v35, 1.0, v35
	v_rcp_f32_e32 v34, v34
	v_rcp_f32_e32 v35, v35
	s_nop 0
	v_pk_mul_f32 v[140:141], v[34:35], v[32:33]
	v_lshlrev_b32_e32 v32, 16, v181
	v_and_b32_e32 v33, 0xffff0000, v181
	v_mul_f32_e32 v34, 0xbfb8aa3b, v32
	v_mul_f32_e32 v35, 0xbfb8aa3b, v33
	v_exp_f32_e32 v34, v34
	v_exp_f32_e32 v35, v35
	v_add_f32_e32 v34, 1.0, v34
	v_add_f32_e32 v35, 1.0, v35
	v_rcp_f32_e32 v34, v34
	v_rcp_f32_e32 v35, v35
	s_nop 0
	v_pk_mul_f32 v[126:127], v[34:35], v[32:33]
	v_pk_mul_f32 v[34:35], v[144:145], v[128:129]
	v_pk_mul_f32 v[32:33], v[144:145], v[134:135]
	v_pk_fma_f32 v[128:129], v[36:37], v[72:73], v[34:35] op_sel_hi:[1,0,1] neg_lo:[0,0,1] neg_hi:[0,0,1]
	v_lshlrev_b32_e32 v34, 16, v186
	v_and_b32_e32 v35, 0xffff0000, v186
	v_mul_f32_e32 v36, 0xbfb8aa3b, v34
	v_mul_f32_e32 v37, 0xbfb8aa3b, v35
	v_exp_f32_e32 v36, v36
	v_exp_f32_e32 v37, v37
	v_pk_fma_f32 v[32:33], v[38:39], v[72:73], v[32:33] op_sel_hi:[1,0,1] neg_lo:[0,0,1] neg_hi:[0,0,1]
	v_pk_mul_f32 v[182:183], v[128:129], v[128:129]
	v_add_f32_e32 v36, 1.0, v36
	v_add_f32_e32 v37, 1.0, v37
	v_rcp_f32_e32 v36, v36
	v_rcp_f32_e32 v37, v37
	v_pk_mul_f32 v[180:181], v[32:33], v[32:33]
	v_pk_mul_f32 v[134:135], v[36:37], v[34:35]
	v_lshlrev_b32_e32 v34, 16, v187
	v_and_b32_e32 v35, 0xffff0000, v187
	v_mul_f32_e32 v36, 0xbfb8aa3b, v34
	v_mul_f32_e32 v37, 0xbfb8aa3b, v35
	v_exp_f32_e32 v36, v36
	v_exp_f32_e32 v37, v37
	v_add_f32_e32 v36, 1.0, v36
	v_add_f32_e32 v37, 1.0, v37
	v_rcp_f32_e32 v36, v36
	v_rcp_f32_e32 v37, v37
	s_nop 0
	v_pk_mul_f32 v[38:39], v[36:37], v[34:35]
	v_pk_mul_f32 v[36:37], v[144:145], v[130:131]
	v_pk_mul_f32 v[34:35], v[144:145], v[138:139]
	v_pk_fma_f32 v[130:131], v[40:41], v[72:73], v[36:37] op_sel_hi:[1,0,1] neg_lo:[0,0,1] neg_hi:[0,0,1]
	v_lshlrev_b32_e32 v36, 16, v184
	v_and_b32_e32 v37, 0xffff0000, v184
	v_mul_f32_e32 v40, 0xbfb8aa3b, v36
	v_mul_f32_e32 v41, 0xbfb8aa3b, v37
	v_exp_f32_e32 v40, v40
	v_exp_f32_e32 v41, v41
	v_pk_fma_f32 v[34:35], v[42:43], v[72:73], v[34:35] op_sel_hi:[1,0,1] neg_lo:[0,0,1] neg_hi:[0,0,1]
	v_pk_mul_f32 v[42:43], v[144:145], v[142:143]
	v_add_f32_e32 v40, 1.0, v40
	v_add_f32_e32 v41, 1.0, v41
	v_rcp_f32_e32 v40, v40
	v_rcp_f32_e32 v41, v41
	v_pk_mul_f32 v[188:189], v[130:131], v[130:131]
	v_pk_mul_f32 v[186:187], v[34:35], v[34:35]
	v_pk_mul_f32 v[138:139], v[40:41], v[36:37]
	v_lshlrev_b32_e32 v36, 16, v185
	v_and_b32_e32 v37, 0xffff0000, v185
	v_mul_f32_e32 v40, 0xbfb8aa3b, v36
	v_mul_f32_e32 v41, 0xbfb8aa3b, v37
	v_exp_f32_e32 v40, v40
	v_exp_f32_e32 v41, v41
	v_add_f32_e32 v40, 1.0, v40
	v_add_f32_e32 v41, 1.0, v41
	v_rcp_f32_e32 v40, v40
	v_rcp_f32_e32 v41, v41
	s_nop 0
	v_pk_mul_f32 v[40:41], v[40:41], v[36:37]
	v_pk_mul_f32 v[36:37], v[144:145], v[166:167]
	s_nop 0
	v_pk_fma_f32 v[36:37], v[46:47], v[72:73], v[36:37] op_sel_hi:[1,0,1] neg_lo:[0,0,1] neg_hi:[0,0,1]
	v_pk_fma_f32 v[46:47], v[44:45], v[72:73], v[42:43] op_sel_hi:[1,0,1] neg_lo:[0,0,1] neg_hi:[0,0,1]
	v_lshlrev_b32_e32 v42, 16, v178
	v_and_b32_e32 v43, 0xffff0000, v178
	v_mul_f32_e32 v44, 0xbfb8aa3b, v42
	v_mul_f32_e32 v45, 0xbfb8aa3b, v43
	v_exp_f32_e32 v44, v44
	v_exp_f32_e32 v45, v45
	v_pk_mul_f32 v[184:185], v[46:47], v[46:47]
	v_pk_mul_f32 v[166:167], v[36:37], v[36:37]
	v_add_f32_e32 v44, 1.0, v44
	v_add_f32_e32 v45, 1.0, v45
	v_rcp_f32_e32 v44, v44
	v_rcp_f32_e32 v45, v45
	s_nop 0
	v_pk_mul_f32 v[142:143], v[44:45], v[42:43]
	v_lshlrev_b32_e32 v42, 16, v179
	v_and_b32_e32 v43, 0xffff0000, v179
	v_mul_f32_e32 v44, 0xbfb8aa3b, v42
	v_mul_f32_e32 v45, 0xbfb8aa3b, v43
	v_exp_f32_e32 v44, v44
	v_exp_f32_e32 v45, v45
	v_add_f32_e32 v44, 1.0, v44
	v_add_f32_e32 v45, 1.0, v45
	v_rcp_f32_e32 v44, v44
	v_rcp_f32_e32 v45, v45
	s_nop 0
	v_pk_mul_f32 v[42:43], v[44:45], v[42:43]
	v_pk_mul_f32 v[44:45], v[144:145], v[148:149]
	s_nop 0
	v_pk_fma_f32 v[18:19], v[18:19], v[72:73], v[44:45] op_sel_hi:[1,0,1] neg_lo:[0,0,1] neg_hi:[0,0,1]
	v_pk_mul_f32 v[44:45], v[144:145], v[136:137]
	v_pk_mul_f32 v[178:179], v[18:19], v[18:19]
	v_pk_fma_f32 v[136:137], v[16:17], v[72:73], v[44:45] op_sel_hi:[1,0,1] neg_lo:[0,0,1] neg_hi:[0,0,1]
	v_lshlrev_b32_e32 v16, 16, v146
	v_and_b32_e32 v17, 0xffff0000, v146
	v_mul_f32_e32 v44, 0xbfb8aa3b, v16
	v_mul_f32_e32 v45, 0xbfb8aa3b, v17
	v_exp_f32_e32 v44, v44
	v_exp_f32_e32 v45, v45
	v_pk_mul_f32 v[190:191], v[136:137], v[136:137]
	v_add_f32_e32 v44, 1.0, v44
	v_add_f32_e32 v45, 1.0, v45
	v_rcp_f32_e32 v44, v44
	v_rcp_f32_e32 v45, v45
	s_nop 0
	v_pk_mul_f32 v[148:149], v[44:45], v[16:17]
	v_lshlrev_b32_e32 v16, 16, v147
	v_and_b32_e32 v17, 0xffff0000, v147
	v_mul_f32_e32 v44, 0xbfb8aa3b, v16
	v_mul_f32_e32 v45, 0xbfb8aa3b, v17
	v_exp_f32_e32 v44, v44
	v_exp_f32_e32 v45, v45
	v_add_f32_e32 v44, 1.0, v44
	v_add_f32_e32 v45, 1.0, v45
	v_rcp_f32_e32 v44, v44
	v_rcp_f32_e32 v45, v45
	s_nop 0
	v_pk_mul_f32 v[44:45], v[44:45], v[16:17]
	v_pk_mul_f32 v[16:17], v[144:145], v[152:153]
	s_nop 0
	v_pk_fma_f32 v[16:17], v[22:23], v[72:73], v[16:17] op_sel_hi:[1,0,1] neg_lo:[0,0,1] neg_hi:[0,0,1]
	v_pk_mul_f32 v[22:23], v[144:145], v[150:151]
	v_pk_mul_f32 v[152:153], v[16:17], v[16:17]
	v_pk_fma_f32 v[146:147], v[20:21], v[72:73], v[22:23] op_sel_hi:[1,0,1] neg_lo:[0,0,1] neg_hi:[0,0,1]
	v_lshlrev_b32_e32 v20, 16, v168
	v_and_b32_e32 v21, 0xffff0000, v168
	v_mul_f32_e32 v22, 0xbfb8aa3b, v20
	v_mul_f32_e32 v23, 0xbfb8aa3b, v21
	v_exp_f32_e32 v22, v22
	v_exp_f32_e32 v23, v23
	v_pk_mul_f32 v[194:195], v[146:147], v[146:147]
	v_add_f32_e32 v22, 1.0, v22
	v_add_f32_e32 v23, 1.0, v23
	v_rcp_f32_e32 v22, v22
	v_rcp_f32_e32 v23, v23
	s_nop 0
	v_pk_mul_f32 v[150:151], v[22:23], v[20:21]
	v_lshlrev_b32_e32 v20, 16, v169
	v_and_b32_e32 v21, 0xffff0000, v169
	v_mul_f32_e32 v22, 0xbfb8aa3b, v20
	v_mul_f32_e32 v23, 0xbfb8aa3b, v21
	v_exp_f32_e32 v22, v22
	v_exp_f32_e32 v23, v23
	v_add_f32_e32 v22, 1.0, v22
	v_add_f32_e32 v23, 1.0, v23
	v_rcp_f32_e32 v22, v22
	v_rcp_f32_e32 v23, v23
	s_nop 0
	v_pk_mul_f32 v[22:23], v[22:23], v[20:21]
	v_pk_mul_f32 v[20:21], v[144:145], v[106:107]
	s_nop 0
	v_pk_fma_f32 v[20:21], v[26:27], v[72:73], v[20:21] op_sel_hi:[1,0,1] neg_lo:[0,0,1] neg_hi:[0,0,1]
	v_pk_mul_f32 v[26:27], v[144:145], v[102:103]
	v_pk_mul_f32 v[168:169], v[20:21], v[20:21]
	v_pk_fma_f32 v[102:103], v[24:25], v[72:73], v[26:27] op_sel_hi:[1,0,1] neg_lo:[0,0,1] neg_hi:[0,0,1]
	v_lshlrev_b32_e32 v24, 16, v160
	v_and_b32_e32 v25, 0xffff0000, v160
	v_mul_f32_e32 v26, 0xbfb8aa3b, v24
	v_mul_f32_e32 v27, 0xbfb8aa3b, v25
	v_exp_f32_e32 v26, v26
	v_exp_f32_e32 v27, v27
	v_pk_mul_f32 v[196:197], v[102:103], v[102:103]
	v_add_f32_e32 v26, 1.0, v26
	v_add_f32_e32 v27, 1.0, v27
	v_rcp_f32_e32 v26, v26
	v_rcp_f32_e32 v27, v27
	s_nop 0
	v_pk_mul_f32 v[106:107], v[26:27], v[24:25]
	v_lshlrev_b32_e32 v24, 16, v161
	v_and_b32_e32 v25, 0xffff0000, v161
	v_mul_f32_e32 v26, 0xbfb8aa3b, v24
	v_mul_f32_e32 v27, 0xbfb8aa3b, v25
	v_exp_f32_e32 v26, v26
	v_exp_f32_e32 v27, v27
	v_add_f32_e32 v26, 1.0, v26
	v_add_f32_e32 v27, 1.0, v27
	v_rcp_f32_e32 v26, v26
	v_rcp_f32_e32 v27, v27
	s_nop 0
	v_pk_mul_f32 v[26:27], v[26:27], v[24:25]
	v_pk_mul_f32 v[24:25], v[144:145], v[92:93]
	s_nop 0
	v_pk_fma_f32 v[24:25], v[30:31], v[72:73], v[24:25] op_sel_hi:[1,0,1] neg_lo:[0,0,1] neg_hi:[0,0,1]
	v_pk_mul_f32 v[30:31], v[144:145], v[90:91]
	v_pk_mul_f32 v[160:161], v[24:25], v[24:25]
	v_pk_fma_f32 v[90:91], v[28:29], v[72:73], v[30:31] op_sel_hi:[1,0,1] neg_lo:[0,0,1] neg_hi:[0,0,1]
	v_lshlrev_b32_e32 v28, 16, v154
	v_and_b32_e32 v29, 0xffff0000, v154
	v_mul_f32_e32 v30, 0xbfb8aa3b, v28
	v_mul_f32_e32 v31, 0xbfb8aa3b, v29
	v_exp_f32_e32 v30, v30
	v_exp_f32_e32 v31, v31
	v_pk_mul_f32 v[198:199], v[90:91], v[90:91]
	v_add_f32_e32 v30, 1.0, v30
	v_add_f32_e32 v31, 1.0, v31
	v_rcp_f32_e32 v30, v30
	v_rcp_f32_e32 v31, v31
	s_nop 0
	v_pk_mul_f32 v[92:93], v[30:31], v[28:29]
	v_lshlrev_b32_e32 v28, 16, v155
	v_and_b32_e32 v29, 0xffff0000, v155
	v_mul_f32_e32 v30, 0xbfb8aa3b, v28
	v_mul_f32_e32 v31, 0xbfb8aa3b, v29
	v_exp_f32_e32 v30, v30
	v_exp_f32_e32 v31, v31
	v_add_f32_e32 v30, 1.0, v30
	v_add_f32_e32 v31, 1.0, v31
	v_rcp_f32_e32 v30, v30
	v_rcp_f32_e32 v31, v31
	s_nop 0
	v_pk_mul_f32 v[28:29], v[30:31], v[28:29]
	v_pk_mul_f32 v[30:31], v[144:145], v[88:89]
	s_nop 0
	v_pk_fma_f32 v[2:3], v[2:3], v[72:73], v[30:31] op_sel_hi:[1,0,1] neg_lo:[0,0,1] neg_hi:[0,0,1]
	v_pk_mul_f32 v[30:31], v[144:145], v[86:87]
	v_pk_mul_f32 v[154:155], v[2:3], v[2:3]
	v_pk_fma_f32 v[86:87], v[0:1], v[72:73], v[30:31] op_sel_hi:[1,0,1] neg_lo:[0,0,1] neg_hi:[0,0,1]
	v_lshlrev_b32_e32 v0, 16, v118
	v_and_b32_e32 v1, 0xffff0000, v118
	v_mul_f32_e32 v30, 0xbfb8aa3b, v0
	v_mul_f32_e32 v31, 0xbfb8aa3b, v1
	v_exp_f32_e32 v30, v30
	v_exp_f32_e32 v31, v31
	v_pk_mul_f32 v[200:201], v[86:87], v[86:87]
	v_add_f32_e32 v30, 1.0, v30
	v_add_f32_e32 v31, 1.0, v31
	v_rcp_f32_e32 v30, v30
	v_rcp_f32_e32 v31, v31
	s_nop 0
	v_pk_mul_f32 v[88:89], v[30:31], v[0:1]
	v_lshlrev_b32_e32 v0, 16, v119
	v_and_b32_e32 v1, 0xffff0000, v119
	v_mul_f32_e32 v30, 0xbfb8aa3b, v0
	v_mul_f32_e32 v31, 0xbfb8aa3b, v1
	v_exp_f32_e32 v30, v30
	v_exp_f32_e32 v31, v31
	v_add_f32_e32 v30, 1.0, v30
	v_add_f32_e32 v31, 1.0, v31
	v_rcp_f32_e32 v30, v30
	v_rcp_f32_e32 v31, v31
	s_nop 0
	v_pk_mul_f32 v[30:31], v[30:31], v[0:1]
	v_pk_mul_f32 v[0:1], v[144:145], v[84:85]
	s_nop 0
	v_pk_fma_f32 v[0:1], v[6:7], v[72:73], v[0:1] op_sel_hi:[1,0,1] neg_lo:[0,0,1] neg_hi:[0,0,1]
	v_pk_mul_f32 v[6:7], v[144:145], v[82:83]
	v_pk_mul_f32 v[84:85], v[0:1], v[0:1]
	v_pk_fma_f32 v[6:7], v[4:5], v[72:73], v[6:7] op_sel_hi:[1,0,1] neg_lo:[0,0,1] neg_hi:[0,0,1]
	v_lshlrev_b32_e32 v4, 16, v94
	v_mul_f32_e32 v73, 0xbfb8aa3b, v4
	v_exp_f32_e32 v73, v73
	v_and_b32_e32 v5, 0xffff0000, v94
	v_pk_mul_f32 v[118:119], v[6:7], v[6:7]
	v_add_f32_e32 v73, 1.0, v73
	v_rcp_f32_e32 v82, v73
	v_mul_f32_e32 v73, 0xbfb8aa3b, v5
	v_exp_f32_e32 v73, v73
	s_nop 0
	v_add_f32_e32 v73, 1.0, v73
	v_rcp_f32_e32 v83, v73
	s_nop 0
	v_pk_mul_f32 v[82:83], v[82:83], v[4:5]
	v_lshlrev_b32_e32 v4, 16, v95
	v_mul_f32_e32 v73, 0xbfb8aa3b, v4
	v_exp_f32_e32 v73, v73
	v_and_b32_e32 v5, 0xffff0000, v95
	v_add_f32_e32 v73, 1.0, v73
	v_rcp_f32_e32 v94, v73
	v_mul_f32_e32 v73, 0xbfb8aa3b, v5
	v_exp_f32_e32 v73, v73
	s_nop 0
	v_add_f32_e32 v73, 1.0, v73
	v_rcp_f32_e32 v95, v73
	v_pk_fma_f32 v[10:11], v[10:11], v[72:73], v[80:81] op_sel_hi:[1,0,1] neg_lo:[0,0,1] neg_hi:[0,0,1]
	v_pk_fma_f32 v[72:73], v[8:9], v[72:73], v[78:79] op_sel_hi:[1,0,1] neg_lo:[0,0,1] neg_hi:[0,0,1]
	v_lshlrev_b32_e32 v78, 16, v70
	v_and_b32_e32 v79, 0xffff0000, v70
	v_mul_f32_e32 v70, 0xbfb8aa3b, v78
	v_exp_f32_e32 v70, v70
	v_pk_mul_f32 v[4:5], v[94:95], v[4:5]
	v_pk_mul_f32 v[8:9], v[72:73], v[72:73]
	v_pk_mul_f32 v[80:81], v[10:11], v[10:11]
	v_add_f32_e32 v70, 1.0, v70
	v_rcp_f32_e32 v94, v70
	v_mul_f32_e32 v70, 0xbfb8aa3b, v79
	v_exp_f32_e32 v70, v70
	s_nop 0
	v_add_f32_e32 v70, 1.0, v70
	v_rcp_f32_e32 v95, v70
	v_add_f32_e32 v70, v116, v117
	v_add_f32_e32 v70, v70, v110
	v_add_f32_e32 v70, v70, v111
	v_add_f32_e32 v70, v70, v158
	v_add_f32_e32 v70, v70, v159
	v_add_f32_e32 v70, v70, v156
	v_add_f32_e32 v70, v70, v157
	v_add_f32_e32 v70, v70, v164
	v_add_f32_e32 v70, v70, v165
	v_add_f32_e32 v70, v70, v162
	v_add_f32_e32 v70, v70, v163
	v_add_f32_e32 v70, v70, v172
	v_add_f32_e32 v70, v70, v173
	v_add_f32_e32 v70, v70, v170
	v_add_f32_e32 v70, v70, v171
	v_add_f32_e32 v70, v70, v176
	v_add_f32_e32 v70, v70, v177
	v_add_f32_e32 v70, v70, v174
	v_add_f32_e32 v70, v70, v175
	v_add_f32_e32 v70, v70, v182
	v_add_f32_e32 v70, v70, v183
	v_add_f32_e32 v70, v70, v180
	v_add_f32_e32 v70, v70, v181
	v_add_f32_e32 v70, v70, v188
	v_add_f32_e32 v70, v70, v189
	v_add_f32_e32 v70, v70, v186
	v_add_f32_e32 v70, v70, v187
	v_add_f32_e32 v70, v70, v184
	v_add_f32_e32 v70, v70, v185
	v_add_f32_e32 v70, v70, v166
	v_add_f32_e32 v70, v70, v167
	v_add_f32_e32 v70, v70, v190
	v_add_f32_e32 v70, v70, v191
	v_add_f32_e32 v70, v70, v178
	v_add_f32_e32 v70, v70, v179
	v_add_f32_e32 v70, v70, v194
	v_add_f32_e32 v70, v70, v195
	v_add_f32_e32 v70, v70, v152
	v_add_f32_e32 v70, v70, v153
	v_add_f32_e32 v70, v70, v196
	v_add_f32_e32 v70, v70, v197
	v_add_f32_e32 v70, v70, v168
	v_add_f32_e32 v70, v70, v169
	v_add_f32_e32 v70, v70, v198
	v_add_f32_e32 v70, v70, v199
	v_add_f32_e32 v70, v70, v160
	v_add_f32_e32 v70, v70, v161
	v_add_f32_e32 v70, v70, v200
	v_add_f32_e32 v70, v70, v201
	v_add_f32_e32 v70, v70, v154
	v_add_f32_e32 v70, v70, v155
	v_add_f32_e32 v70, v70, v118
	v_add_f32_e32 v70, v70, v119
	v_add_f32_e32 v70, v70, v84
	v_add_f32_e32 v70, v70, v85
	v_add_f32_e32 v8, v70, v8
	v_add_f32_e32 v8, v8, v9
	v_add_f32_e32 v8, v8, v80
	v_add_f32_e32 v8, v8, v81
	v_add_f32_e32 v8, v8, v74
	v_add_f32_e32 v8, v8, v75
	v_add_f32_e32 v8, v8, v76
	v_add_f32_e32 v8, v8, v77
	ds_bpermute_b32 v9, v218, v8
	v_pk_mul_f32 v[78:79], v[94:95], v[78:79]
	s_waitcnt lgkmcnt(0)
	v_add_f32_e32 v8, v8, v9
	v_fmamk_f32 v8, v8, 0x3c000000, v207
	v_cmp_gt_f32_e32 vcc, s2, v8
	v_mul_f32_e32 v9, 0x4b800000, v8
	s_nop 0
	v_cndmask_b32_e32 v8, v8, v9, vcc
	v_rsq_f32_e32 v8, v8
	s_nop 0
	v_mul_f32_e32 v9, 0x45800000, v8
	v_cndmask_b32_e32 v8, v8, v9, vcc
	v_mul_f32_e32 v8, v204, v8
	v_pk_mul_f32 v[74:75], v[96:97], v[8:9] op_sel_hi:[1,0]
	v_pk_mul_f32 v[50:51], v[50:51], v[8:9] op_sel_hi:[1,0]
	v_pk_mul_f32 v[12:13], v[74:75], v[12:13]
	v_pk_mul_f32 v[14:15], v[50:51], v[14:15]
	v_pk_mul_f32 v[12:13], v[98:99], v[12:13]
	v_pk_mul_f32 v[14:15], v[100:101], v[14:15]
	v_cvt_pk_bf16_f32 v12, v12, v13
	v_cvt_pk_bf16_f32 v13, v14, v15
	flat_store_dwordx2 v[48:49], v[12:13] offset:1024
	global_load_dwordx4 v[252:255], v205, s[0:1] offset:128
	v_pk_mul_f32 v[50:51], v[52:53], v[8:9] op_sel_hi:[1,0]
	v_pk_mul_f32 v[32:33], v[32:33], v[8:9] op_sel_hi:[1,0]
	v_pk_mul_f32 v[18:19], v[18:19], v[8:9] op_sel_hi:[1,0]
	v_pk_mul_f32 v[16:17], v[16:17], v[8:9] op_sel_hi:[1,0]
	v_pk_mul_f32 v[2:3], v[2:3], v[8:9] op_sel_hi:[1,0]
	v_pk_mul_f32 v[0:1], v[0:1], v[8:9] op_sel_hi:[1,0]
	v_pk_mul_f32 v[10:11], v[10:11], v[8:9] op_sel_hi:[1,0]
	v_pk_mul_f32 v[12:13], v[50:51], v[240:241]
	v_pk_mul_f32 v[50:51], v[54:55], v[8:9] op_sel_hi:[1,0]
	v_pk_mul_f32 v[12:13], v[104:105], v[12:13]
	v_pk_mul_f32 v[14:15], v[50:51], v[242:243]
	v_cvt_pk_bf16_f32 v12, v12, v13
	v_pk_mul_f32 v[14:15], v[108:109], v[14:15]
	v_pk_mul_f32 v[50:51], v[56:57], v[8:9] op_sel_hi:[1,0]
	v_cvt_pk_bf16_f32 v13, v14, v15
	flat_store_dwordx2 v[48:49], v[12:13] offset:1040
	global_load_dwordx4 v[240:243], v205, s[0:1] offset:160
	v_pk_mul_f32 v[12:13], v[50:51], v[244:245]
	v_pk_mul_f32 v[50:51], v[58:59], v[8:9] op_sel_hi:[1,0]
	v_pk_mul_f32 v[12:13], v[112:113], v[12:13]
	v_pk_mul_f32 v[14:15], v[50:51], v[246:247]
	v_cvt_pk_bf16_f32 v12, v12, v13
	v_pk_mul_f32 v[14:15], v[114:115], v[14:15]
	v_pk_mul_f32 v[50:51], v[60:61], v[8:9] op_sel_hi:[1,0]
	v_cvt_pk_bf16_f32 v13, v14, v15
	flat_store_dwordx2 v[48:49], v[12:13] offset:1056
	global_load_dwordx4 v[244:247], v205, s[0:1] offset:192
	v_pk_mul_f32 v[12:13], v[50:51], v[248:249]
	v_pk_mul_f32 v[50:51], v[62:63], v[8:9] op_sel_hi:[1,0]
	v_pk_mul_f32 v[12:13], v[120:121], v[12:13]
	v_pk_mul_f32 v[14:15], v[50:51], v[250:251]
	v_cvt_pk_bf16_f32 v12, v12, v13
	v_pk_mul_f32 v[14:15], v[124:125], v[14:15]
	v_pk_mul_f32 v[50:51], v[132:133], v[8:9] op_sel_hi:[1,0]
	v_cvt_pk_bf16_f32 v13, v14, v15
	flat_store_dwordx2 v[48:49], v[12:13] offset:1072
	global_load_dwordx4 v[248:251], v205, s[0:1] offset:224
	s_waitcnt vmcnt(6)
	v_pk_mul_f32 v[12:13], v[50:51], v[252:253]
	v_pk_mul_f32 v[50:51], v[122:123], v[8:9] op_sel_hi:[1,0]
	v_pk_mul_f32 v[12:13], v[140:141], v[12:13]
	v_pk_mul_f32 v[14:15], v[50:51], v[254:255]
	v_cvt_pk_bf16_f32 v12, v12, v13
	v_pk_mul_f32 v[14:15], v[126:127], v[14:15]
	v_pk_mul_f32 v[50:51], v[128:129], v[8:9] op_sel_hi:[1,0]
	v_cvt_pk_bf16_f32 v13, v14, v15
	flat_store_dwordx2 v[48:49], v[12:13] offset:1088
	global_load_dwordx4 v[252:255], v205, s[0:1] offset:256
	s_waitcnt vmcnt(6)
	v_pk_mul_f32 v[12:13], v[50:51], v[240:241]
	v_pk_mul_f32 v[14:15], v[32:33], v[242:243]
	v_pk_mul_f32 v[12:13], v[134:135], v[12:13]
	v_pk_mul_f32 v[14:15], v[38:39], v[14:15]
	v_cvt_pk_bf16_f32 v12, v12, v13
	v_cvt_pk_bf16_f32 v13, v14, v15
	flat_store_dwordx2 v[48:49], v[12:13] offset:1104
	global_load_dwordx4 v[240:243], v205, s[0:1] offset:288
	v_pk_mul_f32 v[32:33], v[130:131], v[8:9] op_sel_hi:[1,0]
	s_waitcnt vmcnt(6)
	v_pk_mul_f32 v[12:13], v[32:33], v[244:245]
	v_pk_mul_f32 v[32:33], v[34:35], v[8:9] op_sel_hi:[1,0]
	v_pk_mul_f32 v[12:13], v[138:139], v[12:13]
	v_pk_mul_f32 v[14:15], v[32:33], v[246:247]
	v_cvt_pk_bf16_f32 v12, v12, v13
	v_pk_mul_f32 v[14:15], v[40:41], v[14:15]
	v_pk_mul_f32 v[32:33], v[46:47], v[8:9] op_sel_hi:[1,0]
	v_cvt_pk_bf16_f32 v13, v14, v15
	flat_store_dwordx2 v[48:49], v[12:13] offset:1120
	global_load_dwordx4 v[244:247], v205, s[0:1] offset:320
	s_waitcnt vmcnt(6)
	v_pk_mul_f32 v[12:13], v[32:33], v[248:249]
	v_pk_mul_f32 v[32:33], v[36:37], v[8:9] op_sel_hi:[1,0]
	v_pk_mul_f32 v[12:13], v[142:143], v[12:13]
	v_pk_mul_f32 v[14:15], v[32:33], v[250:251]
	v_cvt_pk_bf16_f32 v12, v12, v13
	v_pk_mul_f32 v[14:15], v[42:43], v[14:15]
	v_pk_mul_f32 v[32:33], v[136:137], v[8:9] op_sel_hi:[1,0]
	v_cvt_pk_bf16_f32 v13, v14, v15
	flat_store_dwordx2 v[48:49], v[12:13] offset:1136
	global_load_dwordx4 v[248:251], v205, s[0:1] offset:352
	s_waitcnt vmcnt(6)
	v_pk_mul_f32 v[12:13], v[32:33], v[252:253]
	v_pk_mul_f32 v[14:15], v[18:19], v[254:255]
	v_pk_mul_f32 v[12:13], v[148:149], v[12:13]
	v_pk_mul_f32 v[14:15], v[44:45], v[14:15]
	v_cvt_pk_bf16_f32 v12, v12, v13
	v_cvt_pk_bf16_f32 v13, v14, v15
	flat_store_dwordx2 v[48:49], v[12:13] offset:1152
	global_load_dwordx4 v[252:255], v205, s[0:1] offset:384
	v_pk_mul_f32 v[18:19], v[146:147], v[8:9] op_sel_hi:[1,0]
	s_waitcnt vmcnt(6)
	v_pk_mul_f32 v[14:15], v[16:17], v[242:243]
	v_pk_mul_f32 v[12:13], v[18:19], v[240:241]
	v_pk_mul_f32 v[14:15], v[22:23], v[14:15]
	v_pk_mul_f32 v[12:13], v[150:151], v[12:13]
	v_pk_mul_f32 v[16:17], v[102:103], v[8:9] op_sel_hi:[1,0]
	v_cvt_pk_bf16_f32 v12, v12, v13
	v_cvt_pk_bf16_f32 v13, v14, v15
	flat_store_dwordx2 v[48:49], v[12:13] offset:1168
	global_load_dwordx4 v[240:243], v205, s[0:1] offset:416
	s_waitcnt vmcnt(6)
	v_pk_mul_f32 v[12:13], v[16:17], v[244:245]
	v_pk_mul_f32 v[16:17], v[20:21], v[8:9] op_sel_hi:[1,0]
	v_pk_mul_f32 v[12:13], v[106:107], v[12:13]
	v_pk_mul_f32 v[14:15], v[16:17], v[246:247]
	v_cvt_pk_bf16_f32 v12, v12, v13
	v_pk_mul_f32 v[14:15], v[26:27], v[14:15]
	v_pk_mul_f32 v[16:17], v[90:91], v[8:9] op_sel_hi:[1,0]
	v_cvt_pk_bf16_f32 v13, v14, v15
	flat_store_dwordx2 v[48:49], v[12:13] offset:1184
	global_load_dwordx4 v[244:247], v205, s[0:1] offset:448
	s_waitcnt vmcnt(6)
	v_pk_mul_f32 v[12:13], v[16:17], v[248:249]
	v_pk_mul_f32 v[16:17], v[24:25], v[8:9] op_sel_hi:[1,0]
	v_pk_mul_f32 v[12:13], v[92:93], v[12:13]
	v_pk_mul_f32 v[14:15], v[16:17], v[250:251]
	v_cvt_pk_bf16_f32 v12, v12, v13
	v_pk_mul_f32 v[14:15], v[28:29], v[14:15]
	v_pk_mul_f32 v[16:17], v[86:87], v[8:9] op_sel_hi:[1,0]
	v_cvt_pk_bf16_f32 v13, v14, v15
	flat_store_dwordx2 v[48:49], v[12:13] offset:1200
	global_load_dwordx4 v[248:251], v205, s[0:1] offset:480
	s_waitcnt vmcnt(6)
	v_pk_mul_f32 v[12:13], v[16:17], v[252:253]
	v_pk_mul_f32 v[2:3], v[2:3], v[254:255]
	v_pk_mul_f32 v[12:13], v[88:89], v[12:13]
	v_pk_mul_f32 v[2:3], v[30:31], v[2:3]
	v_cvt_pk_bf16_f32 v12, v12, v13
	v_cvt_pk_bf16_f32 v13, v2, v3
	flat_store_dwordx2 v[48:49], v[12:13] offset:1216
	v_pk_mul_f32 v[2:3], v[6:7], v[8:9] op_sel_hi:[1,0]
	s_waitcnt vmcnt(5)
	v_pk_mul_f32 v[0:1], v[0:1], v[242:243]
	v_pk_mul_f32 v[2:3], v[2:3], v[240:241]
	v_pk_mul_f32 v[0:1], v[4:5], v[0:1]
	v_pk_mul_f32 v[2:3], v[82:83], v[2:3]
	v_pk_mul_f32 v[4:5], v[72:73], v[8:9] op_sel_hi:[1,0]
	v_cvt_pk_bf16_f32 v2, v2, v3
	v_cvt_pk_bf16_f32 v3, v0, v1
	flat_store_dwordx2 v[48:49], v[2:3] offset:1232
	s_waitcnt vmcnt(4)
	v_pk_mul_f32 v[0:1], v[4:5], v[244:245]
	s_nop 0
	v_pk_mul_f32 v[0:1], v[78:79], v[0:1]
	v_lshlrev_b32_e32 v4, 16, v71
	v_cvt_pk_bf16_f32 v0, v0, v1
	v_mul_f32_e32 v1, 0xbfb8aa3b, v4
	v_exp_f32_e32 v1, v1
	v_and_b32_e32 v5, 0xffff0000, v71
	v_pk_mul_f32 v[2:3], v[10:11], v[246:247]
	v_pk_mul_f32 v[10:11], v[66:67], v[8:9] op_sel_hi:[1,0]
	v_add_f32_e32 v1, 1.0, v1
	v_rcp_f32_e32 v6, v1
	v_mul_f32_e32 v1, 0xbfb8aa3b, v5
	v_exp_f32_e32 v1, v1
	v_pk_mul_f32 v[8:9], v[64:65], v[8:9] op_sel_hi:[1,0]
	v_add_f32_e32 v1, 1.0, v1
	v_rcp_f32_e32 v7, v1
	s_nop 0
	v_pk_mul_f32 v[4:5], v[6:7], v[4:5]
	s_nop 0
	v_pk_mul_f32 v[2:3], v[4:5], v[2:3]
	v_lshlrev_b32_e32 v4, 16, v68
	v_cvt_pk_bf16_f32 v1, v2, v3
	flat_store_dwordx2 v[48:49], v[0:1] offset:1248
	v_and_b32_e32 v5, 0xffff0000, v68
	v_mul_f32_e32 v6, 0xbfb8aa3b, v4
	v_mul_f32_e32 v7, 0xbfb8aa3b, v5
	v_exp_f32_e32 v6, v6
	v_exp_f32_e32 v7, v7
	v_add_f32_e32 v6, 1.0, v6
	v_add_f32_e32 v7, 1.0, v7
	v_rcp_f32_e32 v6, v6
	v_rcp_f32_e32 v7, v7
	s_waitcnt vmcnt(3)
	v_pk_mul_f32 v[0:1], v[10:11], v[248:249]
	v_pk_mul_f32 v[4:5], v[6:7], v[4:5]
	v_pk_mul_f32 v[2:3], v[8:9], v[250:251]
	v_pk_mul_f32 v[0:1], v[4:5], v[0:1]
	v_lshlrev_b32_e32 v4, 16, v69
	v_cvt_pk_bf16_f32 v0, v0, v1
	v_mul_f32_e32 v1, 0xbfb8aa3b, v4
	v_exp_f32_e32 v1, v1
	v_and_b32_e32 v5, 0xffff0000, v69
	v_add_f32_e32 v1, 1.0, v1
	v_rcp_f32_e32 v6, v1
	v_mul_f32_e32 v1, 0xbfb8aa3b, v5
	v_exp_f32_e32 v1, v1
	s_nop 0
	v_add_f32_e32 v1, 1.0, v1
	v_rcp_f32_e32 v7, v1
	s_nop 0
	v_pk_mul_f32 v[4:5], v[6:7], v[4:5]
	s_nop 0
	v_pk_mul_f32 v[2:3], v[4:5], v[2:3]
	s_nop 0
	v_cvt_pk_bf16_f32 v1, v2, v3
	flat_store_dwordx2 v[48:49], v[0:1] offset:1264
	s_branch .LBB0_829

.LBB0_857:
	v_pk_add_f32 v[32:33], v[48:49], 0 op_sel_hi:[1,0]
	v_pk_add_f32 v[34:35], v[64:65], 0 op_sel_hi:[1,0]
	v_pk_add_f32 v[32:33], v[50:51], v[32:33]
	v_pk_add_f32 v[34:35], v[66:67], v[34:35]
	v_pk_add_f32 v[32:33], v[52:53], v[32:33]
	v_pk_add_f32 v[34:35], v[68:69], v[34:35]
	v_pk_add_f32 v[32:33], v[54:55], v[32:33]
	v_pk_add_f32 v[34:35], v[70:71], v[34:35]
	v_pk_add_f32 v[32:33], v[56:57], v[32:33]
	v_pk_add_f32 v[34:35], v[72:73], v[34:35]
	v_pk_add_f32 v[32:33], v[58:59], v[32:33]
	v_pk_add_f32 v[34:35], v[74:75], v[34:35]
	v_pk_add_f32 v[32:33], v[60:61], v[32:33]
	v_pk_add_f32 v[34:35], v[76:77], v[34:35]
	v_pk_add_f32 v[32:33], v[62:63], v[32:33]
	v_pk_add_f32 v[34:35], v[78:79], v[34:35]
	s_movk_i32 s2, 0x1400
	v_pk_add_f32 v[32:33], v[34:35], v[32:33]
	v_mov_b64_e32 v[34:35], s[14:15]
	v_mad_u64_u32 v[34:35], s[0:1], v116, s2, v[34:35]
	v_mov_b32_e32 v36, v35
	v_add_f32_e32 v32, v32, v33
	v_mad_u64_u32 v[36:37], s[0:1], v117, s2, v[36:37]
	v_add_f32_e32 v38, v96, v32
	v_mov_b32_e32 v35, v36
	v_lshl_add_u64 v[48:49], v[34:35], 0, s[40:41]
	ds_bpermute_b32 v34, v218, v38
	v_lshl_add_u64 v[32:33], v[118:119], 0, s[40:41]
	v_mov_b32_e32 v115, v193
	v_lshl_add_u64 v[32:33], v[32:33], 0, v[114:115]
	s_mov_b64 s[0:1], 0x1c00
	s_movk_i32 s8, 0x1000
	s_waitcnt lgkmcnt(0)
	v_add_f32_e32 v52, v38, v34
	v_lshl_add_u64 v[34:35], v[32:33], 0, s[0:1]
	v_add_co_u32_e32 v32, vcc, s8, v32
	s_nop 1
	v_addc_co_u32_e32 v33, vcc, 0, v33, vcc
	s_barrier
	s_barrier
	global_load_dwordx2 v[50:51], v[32:33], off offset:3072
	global_load_dwordx2 v[46:47], v[34:35], off offset:16
	global_load_dwordx2 v[44:45], v[34:35], off offset:32
	global_load_dwordx2 v[42:43], v[34:35], off offset:48
	global_load_dwordx2 v[40:41], v[34:35], off offset:64
	global_load_dwordx2 v[38:39], v[34:35], off offset:80
	global_load_dwordx2 v[36:37], v[34:35], off offset:96
	s_nop 0
	global_load_dwordx2 v[34:35], v[34:35], off offset:112
	v_rcp_f32_e32 v32, v52
	v_readlane_b32 s0, v239, 35
	s_add_i32 s16, s16, s0
	v_readlane_b32 s0, v239, 11
	s_add_i32 s11, s11, s0
	s_cmpk_gt_i32 s16, 0xff
	v_readlane_b32 s1, v239, 36
	s_waitcnt vmcnt(0) lgkmcnt(0)
	v_lshlrev_b32_e32 v52, 16, v50
	v_mul_f32_e32 v33, 0xbfb8aa3b, v52
	v_exp_f32_e32 v33, v33
	v_and_b32_e32 v53, 0xffff0000, v50
	v_add_f32_e32 v33, 1.0, v33
	v_rcp_f32_e32 v54, v33
	v_pk_mul_f32 v[0:1], v[0:1], v[32:33] op_sel_hi:[1,0]
	v_mul_f32_e32 v33, 0xbfb8aa3b, v53
	v_exp_f32_e32 v33, v33
	s_nop 0
	v_add_f32_e32 v33, 1.0, v33
	v_rcp_f32_e32 v55, v33
	s_nop 0
	v_pk_mul_f32 v[52:53], v[54:55], v[52:53]
	s_nop 0
	v_pk_mul_f32 v[0:1], v[0:1], v[52:53]
	s_nop 0
	v_cvt_pk_bf16_f32 v50, v0, v1
	v_lshlrev_b32_e32 v0, 16, v51
	v_mul_f32_e32 v33, 0xbfb8aa3b, v0
	v_exp_f32_e32 v33, v33
	v_and_b32_e32 v1, 0xffff0000, v51
	v_add_f32_e32 v33, 1.0, v33
	v_rcp_f32_e32 v52, v33
	v_pk_mul_f32 v[2:3], v[2:3], v[32:33] op_sel_hi:[1,0]
	v_mul_f32_e32 v33, 0xbfb8aa3b, v1
	v_exp_f32_e32 v33, v33
	s_nop 0
	v_add_f32_e32 v33, 1.0, v33
	v_rcp_f32_e32 v53, v33
	s_nop 0
	v_pk_mul_f32 v[0:1], v[52:53], v[0:1]
	s_nop 0
	v_pk_mul_f32 v[0:1], v[2:3], v[0:1]
	v_lshlrev_b32_e32 v2, 16, v46
	v_mul_f32_e32 v33, 0xbfb8aa3b, v2
	v_exp_f32_e32 v33, v33
	v_and_b32_e32 v3, 0xffff0000, v46
	v_cvt_pk_bf16_f32 v51, v0, v1
	v_lshl_add_u64 v[0:1], v[48:49], 0, v[114:115]
	v_add_f32_e32 v33, 1.0, v33
	v_rcp_f32_e32 v48, v33
	v_pk_mul_f32 v[4:5], v[4:5], v[32:33] op_sel_hi:[1,0]
	v_mul_f32_e32 v33, 0xbfb8aa3b, v3
	v_exp_f32_e32 v33, v33
	flat_store_dwordx2 v[0:1], v[50:51] offset:2048
	v_add_f32_e32 v33, 1.0, v33
	v_rcp_f32_e32 v49, v33
	v_pk_mul_f32 v[6:7], v[6:7], v[32:33] op_sel_hi:[1,0]
	v_pk_mul_f32 v[2:3], v[48:49], v[2:3]
	s_nop 0
	v_pk_mul_f32 v[2:3], v[4:5], v[2:3]
	v_lshlrev_b32_e32 v4, 16, v47
	v_cvt_pk_bf16_f32 v2, v2, v3
	v_mul_f32_e32 v3, 0xbfb8aa3b, v4
	v_exp_f32_e32 v3, v3
	v_and_b32_e32 v5, 0xffff0000, v47
	v_add_f32_e32 v3, 1.0, v3
	v_rcp_f32_e32 v46, v3
	v_mul_f32_e32 v3, 0xbfb8aa3b, v5
	v_exp_f32_e32 v3, v3
	s_nop 0
	v_add_f32_e32 v3, 1.0, v3
	v_rcp_f32_e32 v47, v3
	s_nop 0
	v_pk_mul_f32 v[4:5], v[46:47], v[4:5]
	s_nop 0
	v_pk_mul_f32 v[4:5], v[6:7], v[4:5]
	v_pk_mul_f32 v[6:7], v[8:9], v[32:33] op_sel_hi:[1,0]
	v_cvt_pk_bf16_f32 v3, v4, v5
	flat_store_dwordx2 v[0:1], v[2:3] offset:2064
	v_lshlrev_b32_e32 v2, 16, v44
	v_and_b32_e32 v3, 0xffff0000, v44
	v_mul_f32_e32 v4, 0xbfb8aa3b, v2
	v_mul_f32_e32 v5, 0xbfb8aa3b, v3
	v_exp_f32_e32 v4, v4
	v_exp_f32_e32 v5, v5
	v_pk_mul_f32 v[8:9], v[10:11], v[32:33] op_sel_hi:[1,0]
	v_add_f32_e32 v4, 1.0, v4
	v_add_f32_e32 v5, 1.0, v5
	v_rcp_f32_e32 v4, v4
	v_rcp_f32_e32 v5, v5
	s_nop 0
	v_pk_mul_f32 v[2:3], v[4:5], v[2:3]
	s_nop 0
	v_pk_mul_f32 v[2:3], v[6:7], v[2:3]
	v_lshlrev_b32_e32 v4, 16, v45
	v_cvt_pk_bf16_f32 v2, v2, v3
	v_mul_f32_e32 v3, 0xbfb8aa3b, v4
	v_exp_f32_e32 v3, v3
	v_and_b32_e32 v5, 0xffff0000, v45
	v_add_f32_e32 v3, 1.0, v3
	v_rcp_f32_e32 v6, v3
	v_mul_f32_e32 v3, 0xbfb8aa3b, v5
	v_exp_f32_e32 v3, v3
	s_nop 0
	v_add_f32_e32 v3, 1.0, v3
	v_rcp_f32_e32 v7, v3
	s_nop 0
	v_pk_mul_f32 v[4:5], v[6:7], v[4:5]
	s_nop 0
	v_pk_mul_f32 v[4:5], v[8:9], v[4:5]
	v_pk_mul_f32 v[6:7], v[12:13], v[32:33] op_sel_hi:[1,0]
	v_cvt_pk_bf16_f32 v3, v4, v5
	flat_store_dwordx2 v[0:1], v[2:3] offset:2080
	v_lshlrev_b32_e32 v2, 16, v42
	v_and_b32_e32 v3, 0xffff0000, v42
	v_mul_f32_e32 v4, 0xbfb8aa3b, v2
	v_mul_f32_e32 v5, 0xbfb8aa3b, v3
	v_exp_f32_e32 v4, v4
	v_exp_f32_e32 v5, v5
	v_pk_mul_f32 v[8:9], v[14:15], v[32:33] op_sel_hi:[1,0]
	v_add_f32_e32 v4, 1.0, v4
	v_add_f32_e32 v5, 1.0, v5
	v_rcp_f32_e32 v4, v4
	v_rcp_f32_e32 v5, v5
	s_nop 0
	v_pk_mul_f32 v[2:3], v[4:5], v[2:3]
	s_nop 0
	v_pk_mul_f32 v[2:3], v[6:7], v[2:3]
	v_lshlrev_b32_e32 v4, 16, v43
	v_cvt_pk_bf16_f32 v2, v2, v3
	v_mul_f32_e32 v3, 0xbfb8aa3b, v4
	v_exp_f32_e32 v3, v3
	v_and_b32_e32 v5, 0xffff0000, v43
	v_add_f32_e32 v3, 1.0, v3
	v_rcp_f32_e32 v6, v3
	v_mul_f32_e32 v3, 0xbfb8aa3b, v5
	v_exp_f32_e32 v3, v3
	s_nop 0
	v_add_f32_e32 v3, 1.0, v3
	v_rcp_f32_e32 v7, v3
	s_nop 0
	v_pk_mul_f32 v[4:5], v[6:7], v[4:5]
	s_nop 0
	v_pk_mul_f32 v[4:5], v[8:9], v[4:5]
	v_pk_mul_f32 v[6:7], v[16:17], v[32:33] op_sel_hi:[1,0]
	v_cvt_pk_bf16_f32 v3, v4, v5
	flat_store_dwordx2 v[0:1], v[2:3] offset:2096
	v_lshlrev_b32_e32 v2, 16, v40
	v_and_b32_e32 v3, 0xffff0000, v40
	v_mul_f32_e32 v4, 0xbfb8aa3b, v2
	v_mul_f32_e32 v5, 0xbfb8aa3b, v3
	v_exp_f32_e32 v4, v4
	v_exp_f32_e32 v5, v5
	v_pk_mul_f32 v[8:9], v[18:19], v[32:33] op_sel_hi:[1,0]
	v_add_f32_e32 v4, 1.0, v4
	v_add_f32_e32 v5, 1.0, v5
	v_rcp_f32_e32 v4, v4
	v_rcp_f32_e32 v5, v5
	s_nop 0
	v_pk_mul_f32 v[2:3], v[4:5], v[2:3]
	s_nop 0
	v_pk_mul_f32 v[2:3], v[6:7], v[2:3]
	v_lshlrev_b32_e32 v4, 16, v41
	v_cvt_pk_bf16_f32 v2, v2, v3
	v_mul_f32_e32 v3, 0xbfb8aa3b, v4
	v_exp_f32_e32 v3, v3
	v_and_b32_e32 v5, 0xffff0000, v41
	v_add_f32_e32 v3, 1.0, v3
	v_rcp_f32_e32 v6, v3
	v_mul_f32_e32 v3, 0xbfb8aa3b, v5
	v_exp_f32_e32 v3, v3
	s_nop 0
	v_add_f32_e32 v3, 1.0, v3
	v_rcp_f32_e32 v7, v3
	s_nop 0
	v_pk_mul_f32 v[4:5], v[6:7], v[4:5]
	s_nop 0
	v_pk_mul_f32 v[4:5], v[8:9], v[4:5]
	v_pk_mul_f32 v[6:7], v[20:21], v[32:33] op_sel_hi:[1,0]
	v_cvt_pk_bf16_f32 v3, v4, v5
	flat_store_dwordx2 v[0:1], v[2:3] offset:2112
	v_lshlrev_b32_e32 v2, 16, v38
	v_and_b32_e32 v3, 0xffff0000, v38
	v_mul_f32_e32 v4, 0xbfb8aa3b, v2
	v_mul_f32_e32 v5, 0xbfb8aa3b, v3
	v_exp_f32_e32 v4, v4
	v_exp_f32_e32 v5, v5
	v_pk_mul_f32 v[8:9], v[22:23], v[32:33] op_sel_hi:[1,0]
	v_add_f32_e32 v4, 1.0, v4
	v_add_f32_e32 v5, 1.0, v5
	v_rcp_f32_e32 v4, v4
	v_rcp_f32_e32 v5, v5
	s_nop 0
	v_pk_mul_f32 v[2:3], v[4:5], v[2:3]
	s_nop 0
	v_pk_mul_f32 v[2:3], v[6:7], v[2:3]
	v_lshlrev_b32_e32 v4, 16, v39
	v_cvt_pk_bf16_f32 v2, v2, v3
	v_mul_f32_e32 v3, 0xbfb8aa3b, v4
	v_exp_f32_e32 v3, v3
	v_and_b32_e32 v5, 0xffff0000, v39
	v_add_f32_e32 v3, 1.0, v3
	v_rcp_f32_e32 v6, v3
	v_mul_f32_e32 v3, 0xbfb8aa3b, v5
	v_exp_f32_e32 v3, v3
	s_nop 0
	v_add_f32_e32 v3, 1.0, v3
	v_rcp_f32_e32 v7, v3
	s_nop 0
	v_pk_mul_f32 v[4:5], v[6:7], v[4:5]
	s_nop 0
	v_pk_mul_f32 v[4:5], v[8:9], v[4:5]
	v_pk_mul_f32 v[6:7], v[24:25], v[32:33] op_sel_hi:[1,0]
	v_cvt_pk_bf16_f32 v3, v4, v5
	flat_store_dwordx2 v[0:1], v[2:3] offset:2128
	v_lshlrev_b32_e32 v2, 16, v36
	v_and_b32_e32 v3, 0xffff0000, v36
	v_mul_f32_e32 v4, 0xbfb8aa3b, v2
	v_mul_f32_e32 v5, 0xbfb8aa3b, v3
	v_exp_f32_e32 v4, v4
	v_exp_f32_e32 v5, v5
	v_pk_mul_f32 v[8:9], v[26:27], v[32:33] op_sel_hi:[1,0]
	v_add_f32_e32 v4, 1.0, v4
	v_add_f32_e32 v5, 1.0, v5
	v_rcp_f32_e32 v4, v4
	v_rcp_f32_e32 v5, v5
	s_nop 0
	v_pk_mul_f32 v[2:3], v[4:5], v[2:3]
	s_nop 0
	v_pk_mul_f32 v[2:3], v[6:7], v[2:3]
	v_lshlrev_b32_e32 v4, 16, v37
	v_cvt_pk_bf16_f32 v2, v2, v3
	v_mul_f32_e32 v3, 0xbfb8aa3b, v4
	v_exp_f32_e32 v3, v3
	v_and_b32_e32 v5, 0xffff0000, v37
	v_add_f32_e32 v3, 1.0, v3
	v_rcp_f32_e32 v6, v3
	v_mul_f32_e32 v3, 0xbfb8aa3b, v5
	v_exp_f32_e32 v3, v3
	s_nop 0
	v_add_f32_e32 v3, 1.0, v3
	v_rcp_f32_e32 v7, v3
	s_nop 0
	v_pk_mul_f32 v[4:5], v[6:7], v[4:5]
	s_nop 0
	v_pk_mul_f32 v[4:5], v[8:9], v[4:5]
	v_pk_mul_f32 v[6:7], v[28:29], v[32:33] op_sel_hi:[1,0]
	v_cvt_pk_bf16_f32 v3, v4, v5
	flat_store_dwordx2 v[0:1], v[2:3] offset:2144
	v_lshlrev_b32_e32 v2, 16, v34
	v_and_b32_e32 v3, 0xffff0000, v34
	v_mul_f32_e32 v4, 0xbfb8aa3b, v2
	v_mul_f32_e32 v5, 0xbfb8aa3b, v3
	v_exp_f32_e32 v4, v4
	v_exp_f32_e32 v5, v5
	v_pk_mul_f32 v[8:9], v[30:31], v[32:33] op_sel_hi:[1,0]
	v_add_f32_e32 v4, 1.0, v4
	v_add_f32_e32 v5, 1.0, v5
	v_rcp_f32_e32 v4, v4
	v_rcp_f32_e32 v5, v5
	s_nop 0
	v_pk_mul_f32 v[2:3], v[4:5], v[2:3]
	s_nop 0
	v_pk_mul_f32 v[2:3], v[6:7], v[2:3]
	v_lshlrev_b32_e32 v4, 16, v35
	v_cvt_pk_bf16_f32 v2, v2, v3
	v_mul_f32_e32 v3, 0xbfb8aa3b, v4
	v_exp_f32_e32 v3, v3
	v_and_b32_e32 v5, 0xffff0000, v35
	v_add_f32_e32 v3, 1.0, v3
	v_rcp_f32_e32 v6, v3
	v_mul_f32_e32 v3, 0xbfb8aa3b, v5
	v_exp_f32_e32 v3, v3
	s_nop 0
	v_add_f32_e32 v3, 1.0, v3
	v_rcp_f32_e32 v7, v3
	s_nop 0
	v_pk_mul_f32 v[4:5], v[6:7], v[4:5]
	s_nop 0
	v_pk_mul_f32 v[4:5], v[8:9], v[4:5]
	s_nop 0
	v_cvt_pk_bf16_f32 v3, v4, v5
	flat_store_dwordx2 v[0:1], v[2:3] offset:2160
	s_cbranch_scc1 .LBB0_880
.LBB0_858:
	s_ashr_i32 s0, s16, 3
	s_ashr_i32 s1, s0, 31
	s_lshl_b64 s[4:5], s[0:1], 8
	s_mul_i32 s3, s0, 0x208000
	s_mul_hi_i32 s2, s0, 0x208000
	s_add_u32 s3, s12, s3
	s_addc_u32 s2, s13, s2
	s_and_b32 s6, s11, 0x1c0
	s_lshl_b32 s40, s6, 1
	s_add_u32 s3, s3, s40
	v_mov_b32_e32 v41, v206
	s_addc_u32 s7, s2, 0
	s_add_u32 s2, s3, 0x1800
	v_ashrrev_i32_e32 v0, 31, v41
	v_lshrrev_b32_e32 v0, 29, v0
	s_addc_u32 s3, s7, 0
	s_lshl_b32 s6, s6, 15
	v_add_u32_e32 v2, v41, v0
	s_add_u32 s6, s85, s6
	v_ashrrev_i32_e32 v100, 3, v2
	v_and_b32_e32 v2, -8, v2
	s_addc_u32 s7, s82, 0
	s_lshl_b64 s[0:1], s[0:1], 9
	v_sub_u32_e32 v14, v41, v2
	s_add_u32 s0, s6, s0
	v_mov_b64_e32 v[0:1], s[2:3]
	v_lshlrev_b32_e32 v96, 3, v14
	v_ashrrev_i32_e32 v8, 3, v41
	s_addc_u32 s1, s7, s1
	v_mad_i64_i32 v[0:1], s[6:7], v100, s79, v[0:1]
	v_ashrrev_i32_e32 v97, 31, v96
	v_ashrrev_i32_e32 v9, 31, v8
	v_lshl_add_u64 v[42:43], v[96:97], 1, v[0:1]
	v_lshlrev_b64 v[0:1], 15, v[8:9]
	v_lshlrev_b32_e32 v9, 4, v41
	v_lshl_add_u64 v[0:1], s[0:1], 0, v[0:1]
	v_and_b32_e32 v2, 0x70, v9
	v_mov_b32_e32 v3, v193
	v_lshl_add_u64 v[10:11], v[0:1], 0, v[2:3]
	s_brev_b32 s0, 64
	v_add_co_u32_e32 v4, vcc, s0, v10
	v_mov_b64_e32 v[12:13], s[12:13]
	s_nop 0
	v_addc_co_u32_e32 v5, vcc, 0, v11, vcc
	global_load_dwordx4 v[0:3], v[42:43], off
	s_nop 0
	global_load_dwordx4 v[4:7], v[4:5], off
	v_lshl_add_u64 v[116:117], s[4:5], 0, v[112:113]
	v_lshrrev_b32_e32 v15, 1, v41
	v_lshlrev_b32_e32 v16, 3, v41
	v_mul_lo_u32 v8, v8, s80
	v_mad_u64_u32 v[118:119], s[0:1], v116, s79, v[12:13]
	v_and_b32_e32 v192, 16, v15
	v_and_b32_e32 v9, 0x60, v9
	v_and_b32_e32 v15, 8, v16
	v_add_u32_e32 v12, 0, v8
	v_mov_b32_e32 v8, v119
	v_add3_u32 v101, v12, v9, v15
	v_mad_u64_u32 v[8:9], s[0:1], v117, s79, v[8:9]
	v_mul_lo_u32 v9, v100, s80
	v_mov_b32_e32 v119, v8
	v_add_u32_e32 v12, 0, v9
	v_lshl_add_u64 v[8:9], v[118:119], 0, s[40:41]
	v_lshlrev_b32_e32 v13, 4, v14
	v_lshl_add_u64 v[8:9], v[8:9], 0, v[192:193]
	s_mov_b64 s[0:1], 0x1400
	v_add_u32_e32 v154, v12, v13
	v_lshl_add_u64 v[12:13], v[8:9], 0, s[0:1]
	v_add_co_u32_e32 v8, vcc, s8, v8
	s_mov_b32 s0, 0x82000
	s_nop 0
	v_addc_co_u32_e32 v9, vcc, 0, v9, vcc
	global_load_dwordx4 v[88:91], v[12:13], off offset:32
	global_load_dwordx4 v[84:87], v[12:13], off offset:64
	global_load_dwordx4 v[92:95], v[8:9], off offset:1024
	global_load_dwordx4 v[80:83], v[12:13], off offset:96
	v_add_co_u32_e32 v8, vcc, s0, v42
	v_add_u32_e32 v153, 0x4800, v101
	s_nop 0
	v_addc_co_u32_e32 v9, vcc, 0, v43, vcc
	s_mov_b64 s[0:1], 0x2000000
	v_lshl_add_u64 v[98:99], v[10:11], 0, s[0:1]
	v_and_b32_e32 v56, 31, v41
	v_add_u32_e32 v57, 0, v192
	v_mad_u32_u24 v152, v56, s80, v57
	s_mov_b32 s1, 0x104000
	v_add_co_u32_e32 v42, vcc, s1, v42
	v_readfirstlane_b32 s0, v41
	s_nop 0
	v_addc_co_u32_e32 v43, vcc, 0, v43, vcc
	v_mul_u32_u24_e32 v41, 0x90, v56
	v_add_u32_e32 v115, v57, v41
	s_cmpk_gt_i32 s0, 0xff
	s_cselect_b64 s[4:5], -1, 0
	s_cmpk_lt_i32 s0, 0x100
	v_mov_b32_e32 v40, 0
	s_waitcnt vmcnt(0) lgkmcnt(0)
	ds_write_b128 v154, v[0:3]
	ds_write2_b64 v153, v[4:5], v[6:7] offset1:2
	global_load_dwordx4 v[0:3], v[8:9], off
	global_load_dwordx4 v[4:7], v[98:99], off offset:128
	v_add_u32_e32 v8, 0x6800, v101
	s_waitcnt lgkmcnt(0)
	s_barrier
	s_barrier
	s_cselect_b64 s[0:1], -1, 0
	s_and_b64 vcc, exec, s[4:5]
	v_mov_b32_e32 v56, 0
	v_mov_b32_e32 v57, 0
	v_mov_b32_e32 v58, 0
	v_mov_b32_e32 v59, 0
	v_mov_b32_e32 v60, 0
	v_mov_b32_e32 v61, 0
	v_mov_b32_e32 v62, 0
	v_mov_b32_e32 v63, 0
	s_waitcnt vmcnt(0)
	ds_write_b128 v154, v[0:3] offset:9216
	ds_write2_b64 v8, v[4:5], v[6:7] offset0:128 offset1:130
	ds_read_b128 v[0:3], v152
	ds_read_b128 v[32:35], v152 offset:32
	ds_read_b128 v[16:19], v152 offset:4608
	ds_read_b128 v[36:39], v152 offset:4640
	s_waitcnt lgkmcnt(1)
	v_mfma_f32_32x32x16_bf16 v[16:31], v[16:19], v[92:95], 0
	s_waitcnt lgkmcnt(0)
	v_mfma_f32_32x32x16_bf16 v[16:31], v[36:39], v[88:91], v[16:31]
	ds_read_b128 v[36:39], v152 offset:64
	ds_read_b128 v[44:47], v152 offset:4672
	ds_read_b128 v[48:51], v152 offset:96
	ds_read_b128 v[52:55], v152 offset:4704
	global_load_dwordx4 v[68:71], v[42:43], off
	global_load_dwordx4 v[64:67], v[98:99], off offset:256
	v_mfma_f32_32x32x16_bf16 v[0:15], v[0:3], v[92:95], 0
	v_mfma_f32_32x32x16_bf16 v[0:15], v[32:35], v[88:91], v[0:15]
	v_mov_b32_e32 v32, 0
	v_mov_b32_e32 v33, 0
	v_mov_b32_e32 v34, 0
	v_mov_b32_e32 v35, 0
	s_waitcnt lgkmcnt(0)
	v_mfma_f32_32x32x16_bf16 v[0:15], v[36:39], v[84:87], v[0:15]
	v_mov_b32_e32 v36, 0
	v_mov_b32_e32 v37, 0
	v_mov_b32_e32 v38, 0
	v_mov_b32_e32 v39, 0
	v_mfma_f32_32x32x16_bf16 v[16:31], v[44:47], v[84:87], v[16:31]
	v_mov_b32_e32 v44, 0
	v_mov_b32_e32 v45, 0
	v_mov_b32_e32 v46, 0
	v_mov_b32_e32 v47, 0
	v_mfma_f32_32x32x16_bf16 v[0:15], v[48:51], v[80:83], v[0:15]
	v_mov_b32_e32 v48, 0
	v_mov_b32_e32 v49, 0
	v_mov_b32_e32 v50, 0
	v_mov_b32_e32 v51, 0
	v_mfma_f32_32x32x16_bf16 v[16:31], v[52:55], v[80:83], v[16:31]
	s_nop 6
	v_max_f32_e32 v41, v1, v1
	v_max_f32_e32 v42, v0, v0
	v_max_f32_e32 v41, v42, v41
	v_mov_b32_e32 v52, 0
	v_mov_b32_e32 v53, 0
	v_mov_b32_e32 v54, 0
	v_mov_b32_e32 v55, 0
	v_max3_f32 v43, v2, v3, v17
	v_max3_f32 v41, v41, v16, v18
	v_max3_f32 v42, v43, v6, v7
	v_max3_f32 v41, v41, v19, v4
	v_max3_f32 v42, v42, v22, v23
	v_max3_f32 v41, v41, v5, v20
	v_max3_f32 v42, v42, v10, v11
	v_max3_f32 v41, v41, v21, v8
	v_max3_f32 v42, v42, v26, v27
	v_max3_f32 v41, v41, v9, v24
	v_max3_f32 v42, v42, v14, v15
	v_max3_f32 v41, v41, v25, v12
	v_max3_f32 v42, v42, v30, v31
	v_max3_f32 v41, v41, v13, v28
	v_max3_f32 v41, v41, v29, v42
	v_mov_b32_e32 v42, v41
	s_nop 1
	v_permlane32_swap_b32_e32 v41, v42
	v_max_f32_e32 v42, v42, v42
	v_max_f32_e32 v41, v41, v41
	v_max_f32_e32 v155, v41, v42
	v_sub_f32_e32 v0, v0, v155
	v_sub_f32_e32 v16, v16, v155
	v_sub_f32_e32 v1, v1, v155
	v_sub_f32_e32 v17, v17, v155
	v_sub_f32_e32 v2, v2, v155
	v_sub_f32_e32 v18, v18, v155
	v_sub_f32_e32 v3, v3, v155
	v_sub_f32_e32 v19, v19, v155
	v_sub_f32_e32 v4, v4, v155
	v_sub_f32_e32 v20, v20, v155
	v_sub_f32_e32 v5, v5, v155
	v_sub_f32_e32 v21, v21, v155
	v_sub_f32_e32 v6, v6, v155
	v_sub_f32_e32 v22, v22, v155
	v_sub_f32_e32 v7, v7, v155
	v_sub_f32_e32 v23, v23, v155
	v_sub_f32_e32 v8, v8, v155
	v_sub_f32_e32 v24, v24, v155
	v_sub_f32_e32 v9, v9, v155
	v_sub_f32_e32 v25, v25, v155
	v_sub_f32_e32 v10, v10, v155
	v_sub_f32_e32 v26, v26, v155
	v_sub_f32_e32 v11, v11, v155
	v_sub_f32_e32 v27, v27, v155
	v_sub_f32_e32 v12, v12, v155
	v_sub_f32_e32 v28, v28, v155
	v_sub_f32_e32 v13, v13, v155
	v_sub_f32_e32 v29, v29, v155
	v_sub_f32_e32 v14, v14, v155
	v_sub_f32_e32 v30, v30, v155
	v_sub_f32_e32 v15, v15, v155
	v_sub_f32_e32 v31, v31, v155
	v_exp_f32_e32 v120, v0
	v_exp_f32_e32 v121, v1
	v_exp_f32_e32 v122, v16
	v_exp_f32_e32 v123, v17
	v_exp_f32_e32 v124, v2
	v_exp_f32_e32 v125, v3
	v_exp_f32_e32 v126, v18
	v_exp_f32_e32 v127, v19
	v_exp_f32_e32 v128, v4
	v_exp_f32_e32 v129, v5
	v_exp_f32_e32 v130, v20
	v_exp_f32_e32 v131, v21
	v_exp_f32_e32 v132, v6
	v_exp_f32_e32 v133, v7
	v_exp_f32_e32 v134, v22
	v_exp_f32_e32 v135, v23
	v_exp_f32_e32 v136, v8
	v_exp_f32_e32 v137, v9
	v_exp_f32_e32 v138, v24
	v_exp_f32_e32 v139, v25
	v_exp_f32_e32 v140, v10
	v_exp_f32_e32 v141, v11
	v_exp_f32_e32 v142, v26
	v_exp_f32_e32 v143, v27
	v_exp_f32_e32 v144, v12
	v_exp_f32_e32 v145, v13
	v_exp_f32_e32 v146, v28
	v_exp_f32_e32 v147, v29
	v_exp_f32_e32 v148, v14
	v_exp_f32_e32 v149, v15
	v_exp_f32_e32 v150, v30
	v_exp_f32_e32 v151, v31
	v_cvt_pk_bf16_f32 v104, v120, v121
	v_cvt_pk_bf16_f32 v105, v124, v125
	v_cvt_pk_bf16_f32 v106, v128, v129
	v_cvt_pk_bf16_f32 v107, v132, v133
	v_cvt_pk_bf16_f32 v72, v122, v123
	v_cvt_pk_bf16_f32 v73, v126, v127
	v_cvt_pk_bf16_f32 v74, v130, v131
	v_cvt_pk_bf16_f32 v75, v134, v135
	v_cvt_pk_bf16_f32 v108, v136, v137
	v_cvt_pk_bf16_f32 v109, v140, v141
	v_cvt_pk_bf16_f32 v110, v144, v145
	v_cvt_pk_bf16_f32 v111, v148, v149
	v_cvt_pk_bf16_f32 v76, v138, v139
	v_cvt_pk_bf16_f32 v77, v142, v143
	v_cvt_pk_bf16_f32 v78, v146, v147
	v_cvt_pk_bf16_f32 v79, v150, v151
	v_mov_b32_e32 v41, 0
	v_mov_b32_e32 v42, 0
	v_mov_b32_e32 v43, 0
	v_mov_b32_e32 v0, 0
	v_mov_b32_e32 v1, 0
	v_mov_b32_e32 v2, 0
	v_mov_b32_e32 v3, 0
	v_mov_b32_e32 v4, 0
	v_mov_b32_e32 v5, 0
	v_mov_b32_e32 v6, 0
	v_mov_b32_e32 v7, 0
	v_mov_b32_e32 v8, 0
	v_mov_b32_e32 v9, 0
	v_mov_b32_e32 v10, 0
	v_mov_b32_e32 v11, 0
	v_mov_b32_e32 v12, 0
	v_mov_b32_e32 v13, 0
	v_mov_b32_e32 v14, 0
	v_mov_b32_e32 v15, 0
	v_mov_b32_e32 v16, 0
	v_mov_b32_e32 v17, 0
	v_mov_b32_e32 v18, 0
	v_mov_b32_e32 v19, 0
	v_mov_b32_e32 v20, 0
	v_mov_b32_e32 v21, 0
	v_mov_b32_e32 v22, 0
	v_mov_b32_e32 v23, 0
	v_mov_b32_e32 v24, 0
	v_mov_b32_e32 v25, 0
	v_mov_b32_e32 v26, 0
	v_mov_b32_e32 v27, 0
	v_mov_b32_e32 v28, 0
	v_mov_b32_e32 v29, 0
	v_mov_b32_e32 v30, 0
	v_mov_b32_e32 v31, 0
	s_cbranch_vccnz .LBB0_860
	ds_read_b128 v[240:243], v115 offset:18432
	ds_read_b128 v[244:247], v115 offset:18464
	ds_read_b128 v[248:251], v115 offset:18496
	ds_read_b128 v[252:255], v115 offset:18528
	s_waitcnt lgkmcnt(3)
	v_mfma_f32_32x32x16_bf16 v[32:47], v[240:243], v[104:107], 0
	ds_read_b128 v[240:243], v115 offset:23040
	s_waitcnt lgkmcnt(3)
	v_mfma_f32_32x32x16_bf16 v[32:47], v[244:247], v[108:111], v[32:47]
	s_waitcnt lgkmcnt(2)
	v_mfma_f32_32x32x16_bf16 v[32:47], v[248:251], v[72:75], v[32:47]
	s_waitcnt lgkmcnt(1)
	v_mfma_f32_32x32x16_bf16 v[32:47], v[252:255], v[76:79], v[32:47]
	s_waitcnt lgkmcnt(0)
	v_mfma_f32_32x32x16_bf16 v[48:63], v[240:243], v[104:107], 0
	s_nop 1
	ds_read_b128 v[0:3], v115 offset:23072
	s_nop 7
	v_mov_b32_e32 v4, v36
	v_mov_b32_e32 v5, v37
	v_mov_b32_e32 v6, v38
	v_mov_b32_e32 v7, v39
	v_mov_b32_e32 v8, v40
	v_mov_b32_e32 v9, v41
	s_waitcnt lgkmcnt(0)
	v_mfma_f32_32x32x16_bf16 v[48:63], v[0:3], v[108:111], v[48:63]
	ds_read_b128 v[0:3], v115 offset:23104
	v_mov_b32_e32 v10, v42
	v_mov_b32_e32 v11, v43
	v_mov_b32_e32 v12, v44
	v_mov_b32_e32 v13, v45
	v_mov_b32_e32 v14, v46
	v_mov_b32_e32 v15, v47
	s_waitcnt lgkmcnt(0)
	v_mfma_f32_32x32x16_bf16 v[48:63], v[0:3], v[72:75], v[48:63]
	ds_read_b128 v[0:3], v115 offset:23136
	s_waitcnt lgkmcnt(0)
	v_mfma_f32_32x32x16_bf16 v[48:63], v[0:3], v[76:79], v[48:63]
	v_mov_b32_e32 v0, v32
	v_mov_b32_e32 v1, v33
	v_mov_b32_e32 v2, v34
	v_mov_b32_e32 v3, v35
	s_nop 7
	v_mov_b32_e32 v16, v48
	v_mov_b32_e32 v17, v49
	v_mov_b32_e32 v18, v50
	v_mov_b32_e32 v19, v51
	v_mov_b32_e32 v20, v52
	v_mov_b32_e32 v21, v53
	v_mov_b32_e32 v22, v54
	v_mov_b32_e32 v23, v55
	v_mov_b32_e32 v24, v56
	v_mov_b32_e32 v25, v57
	v_mov_b32_e32 v26, v58
	v_mov_b32_e32 v27, v59
	v_mov_b32_e32 v28, v60
	v_mov_b32_e32 v29, v61
	v_mov_b32_e32 v30, v62
	v_mov_b32_e32 v31, v63
.LBB0_860:
	v_mad_i64_i32 v[102:103], s[6:7], v100, s79, 0
	s_waitcnt lgkmcnt(0)
	s_barrier
	s_barrier
	s_waitcnt vmcnt(0)
	ds_write_b128 v154, v[68:71]
	v_add_u32_e32 v68, 0x9000, v101
	ds_write2_b64 v68, v[64:65], v[66:67] offset1:2
	v_lshl_add_u64 v[64:65], s[2:3], 0, v[102:103]
	v_lshl_add_u64 v[64:65], v[96:97], 1, v[64:65]
	v_add_co_u32_e32 v64, vcc, 0x186000, v64
	s_nop 1
	v_addc_co_u32_e32 v65, vcc, 0, v65, vcc
	global_load_dwordx4 v[100:103], v[64:65], off
	s_nop 0
	global_load_dwordx4 v[96:99], v[98:99], off offset:384
	v_cndmask_b32_e64 v64, 0, 1, s[4:5]
	v_cmp_ne_u32_e64 s[6:7], 1, v64
	s_andn2_b64 vcc, exec, s[4:5]
	s_cbranch_vccnz .LBB0_862
	ds_read_b128 v[240:243], v115 offset:18432
	ds_read_b128 v[244:247], v115 offset:18464
	ds_read_b128 v[248:251], v115 offset:18496
	ds_read_b128 v[252:255], v115 offset:18528
	s_waitcnt lgkmcnt(3)
	v_mfma_f32_32x32x16_bf16 v[32:47], v[240:243], v[104:107], v[32:47]
	ds_read_b128 v[240:243], v115 offset:23040
	s_waitcnt lgkmcnt(3)
	v_mfma_f32_32x32x16_bf16 v[32:47], v[244:247], v[108:111], v[32:47]
	ds_read_b128 v[244:247], v115 offset:23072
	s_waitcnt lgkmcnt(3)
	v_mfma_f32_32x32x16_bf16 v[32:47], v[248:251], v[72:75], v[32:47]
	ds_read_b128 v[248:251], v115 offset:23104
	s_waitcnt lgkmcnt(3)
	v_mfma_f32_32x32x16_bf16 v[32:47], v[252:255], v[76:79], v[32:47]
	ds_read_b128 v[252:255], v115 offset:23136
	s_waitcnt lgkmcnt(3)
	v_mfma_f32_32x32x16_bf16 v[48:63], v[240:243], v[104:107], v[48:63]
	s_waitcnt lgkmcnt(2)
	v_mfma_f32_32x32x16_bf16 v[48:63], v[244:247], v[108:111], v[48:63]
	s_waitcnt lgkmcnt(1)
	v_mfma_f32_32x32x16_bf16 v[48:63], v[248:251], v[72:75], v[48:63]
	s_waitcnt lgkmcnt(0)
	v_mfma_f32_32x32x16_bf16 v[48:63], v[252:255], v[76:79], v[48:63]
	s_nop 5
	v_mov_b64_e32 v[0:1], v[32:33]
	v_mov_b64_e32 v[2:3], v[34:35]
	v_mov_b64_e32 v[4:5], v[36:37]
	v_mov_b64_e32 v[6:7], v[38:39]
	v_mov_b64_e32 v[8:9], v[40:41]
	v_mov_b64_e32 v[10:11], v[42:43]
	v_mov_b64_e32 v[12:13], v[44:45]
	v_mov_b64_e32 v[14:15], v[46:47]
	s_nop 1
	v_mov_b64_e32 v[16:17], v[48:49]
	v_mov_b64_e32 v[18:19], v[50:51]
	v_mov_b64_e32 v[20:21], v[52:53]
	v_mov_b64_e32 v[22:23], v[54:55]
	v_mov_b64_e32 v[24:25], v[56:57]
	v_mov_b64_e32 v[26:27], v[58:59]
	v_mov_b64_e32 v[28:29], v[60:61]
	v_mov_b64_e32 v[30:31], v[62:63]

.LBB0_864:
	v_exp_f32_e32 v106, v48
	v_exp_f32_e32 v107, v49
	v_exp_f32_e32 v64, v64
	v_exp_f32_e32 v65, v65
	v_exp_f32_e32 v50, v50
	v_exp_f32_e32 v51, v51
	v_exp_f32_e32 v66, v66
	v_exp_f32_e32 v67, v67
	v_exp_f32_e32 v52, v52
	v_exp_f32_e32 v53, v53
	v_exp_f32_e32 v68, v68
	v_exp_f32_e32 v69, v69
	v_exp_f32_e32 v54, v54
	v_exp_f32_e32 v55, v55
	v_exp_f32_e32 v70, v70
	v_exp_f32_e32 v71, v71
	v_exp_f32_e32 v56, v56
	v_exp_f32_e32 v57, v57
	v_exp_f32_e32 v72, v72
	v_exp_f32_e32 v73, v73
	v_exp_f32_e32 v58, v58
	v_exp_f32_e32 v59, v59
	v_exp_f32_e32 v74, v74
	v_exp_f32_e32 v75, v75
	v_exp_f32_e32 v60, v60
	v_exp_f32_e32 v61, v61
	v_exp_f32_e32 v76, v76
	v_exp_f32_e32 v77, v77
	v_exp_f32_e32 v62, v62
	v_exp_f32_e32 v63, v63
	v_exp_f32_e32 v78, v78
	v_exp_f32_e32 v79, v79
	v_cndmask_b32_e64 v33, 0, 1, s[0:1]
	v_cvt_pk_bf16_f32 v38, v106, v107
	v_cvt_pk_bf16_f32 v39, v50, v51
	v_cvt_pk_bf16_f32 v40, v52, v53
	v_cvt_pk_bf16_f32 v41, v54, v55
	v_cvt_pk_bf16_f32 v34, v64, v65
	v_cvt_pk_bf16_f32 v35, v66, v67
	v_cvt_pk_bf16_f32 v36, v68, v69
	v_cvt_pk_bf16_f32 v37, v70, v71
	v_cvt_pk_bf16_f32 v46, v56, v57
	v_cvt_pk_bf16_f32 v47, v58, v59
	v_cvt_pk_bf16_f32 v48, v60, v61
	v_cvt_pk_bf16_f32 v49, v62, v63
	v_cvt_pk_bf16_f32 v42, v72, v73
	v_cvt_pk_bf16_f32 v43, v74, v75
	v_cvt_pk_bf16_f32 v44, v76, v77
	v_cmp_ne_u32_e64 s[8:9], 1, v33
	s_andn2_b64 vcc, exec, s[0:1]
	v_cvt_pk_bf16_f32 v45, v78, v79
	s_cbranch_vccnz .LBB0_866
	ds_read_b128 v[240:243], v115 offset:27648
	ds_read_b128 v[244:247], v115 offset:27680
	ds_read_b128 v[248:251], v115 offset:27712
	ds_read_b128 v[252:255], v115 offset:27744
	s_waitcnt lgkmcnt(3)
	v_mfma_f32_32x32x16_bf16 v[0:15], v[240:243], v[38:41], v[0:15]
	ds_read_b128 v[240:243], v115 offset:32256
	s_waitcnt lgkmcnt(3)
	v_mfma_f32_32x32x16_bf16 v[0:15], v[244:247], v[46:49], v[0:15]
	ds_read_b128 v[244:247], v115 offset:32288
	s_waitcnt lgkmcnt(3)
	v_mfma_f32_32x32x16_bf16 v[0:15], v[248:251], v[34:37], v[0:15]
	ds_read_b128 v[248:251], v115 offset:32320
	s_waitcnt lgkmcnt(3)
	v_mfma_f32_32x32x16_bf16 v[0:15], v[252:255], v[42:45], v[0:15]
	ds_read_b128 v[252:255], v115 offset:32352
	s_waitcnt lgkmcnt(3)
	v_mfma_f32_32x32x16_bf16 v[16:31], v[240:243], v[38:41], v[16:31]
	s_waitcnt lgkmcnt(2)
	v_mfma_f32_32x32x16_bf16 v[16:31], v[244:247], v[46:49], v[16:31]
	s_waitcnt lgkmcnt(1)
	v_mfma_f32_32x32x16_bf16 v[16:31], v[248:251], v[34:37], v[16:31]
	s_waitcnt lgkmcnt(0)
	v_mfma_f32_32x32x16_bf16 v[16:31], v[252:255], v[42:45], v[16:31]
	s_nop 7
.LBB0_866:
	s_waitcnt lgkmcnt(0)
	s_barrier
	s_barrier
	s_and_b64 vcc, exec, s[6:7]
	s_waitcnt vmcnt(0)
	ds_write_b128 v154, v[100:103] offset:9216
	ds_write2_b64 v153, v[96:97], v[98:99] offset1:2
	s_cbranch_vccnz .LBB0_868
	ds_read_b128 v[240:243], v115 offset:27648
	ds_read_b128 v[244:247], v115 offset:27680
	ds_read_b128 v[248:251], v115 offset:27712
	ds_read_b128 v[252:255], v115 offset:27744
	s_waitcnt lgkmcnt(3)
	v_mfma_f32_32x32x16_bf16 v[0:15], v[240:243], v[38:41], v[0:15]
	ds_read_b128 v[240:243], v115 offset:32256
	s_waitcnt lgkmcnt(3)
	v_mfma_f32_32x32x16_bf16 v[0:15], v[244:247], v[46:49], v[0:15]
	ds_read_b128 v[244:247], v115 offset:32288
	s_waitcnt lgkmcnt(3)
	v_mfma_f32_32x32x16_bf16 v[0:15], v[248:251], v[34:37], v[0:15]
	ds_read_b128 v[248:251], v115 offset:32320
	s_waitcnt lgkmcnt(3)
	v_mfma_f32_32x32x16_bf16 v[0:15], v[252:255], v[42:45], v[0:15]
	ds_read_b128 v[252:255], v115 offset:32352
	s_waitcnt lgkmcnt(3)
	v_mfma_f32_32x32x16_bf16 v[16:31], v[240:243], v[38:41], v[16:31]
	s_waitcnt lgkmcnt(2)
	v_mfma_f32_32x32x16_bf16 v[16:31], v[244:247], v[46:49], v[16:31]
	s_waitcnt lgkmcnt(1)
	v_mfma_f32_32x32x16_bf16 v[16:31], v[248:251], v[34:37], v[16:31]
	s_waitcnt lgkmcnt(0)
	v_mfma_f32_32x32x16_bf16 v[16:31], v[252:255], v[42:45], v[16:31]
	s_nop 7

.LBB0_870:
	v_exp_f32_e32 v64, v64
	v_exp_f32_e32 v65, v65
	v_exp_f32_e32 v96, v48
	v_exp_f32_e32 v97, v49
	v_exp_f32_e32 v66, v66
	v_exp_f32_e32 v67, v67
	v_exp_f32_e32 v98, v50
	v_exp_f32_e32 v99, v51
	v_exp_f32_e32 v68, v68
	v_exp_f32_e32 v69, v69
	v_exp_f32_e32 v100, v52
	v_exp_f32_e32 v101, v53
	v_exp_f32_e32 v70, v70
	v_exp_f32_e32 v71, v71
	v_exp_f32_e32 v102, v54
	v_exp_f32_e32 v103, v55
	v_exp_f32_e32 v72, v72
	v_exp_f32_e32 v73, v73
	v_exp_f32_e32 v104, v56
	v_exp_f32_e32 v105, v57
	v_exp_f32_e32 v74, v74
	v_exp_f32_e32 v75, v75
	v_exp_f32_e32 v106, v58
	v_exp_f32_e32 v107, v59
	v_exp_f32_e32 v76, v76
	v_exp_f32_e32 v77, v77
	v_exp_f32_e32 v108, v60
	v_exp_f32_e32 v109, v61
	v_exp_f32_e32 v78, v78
	v_exp_f32_e32 v79, v79
	v_exp_f32_e32 v110, v62
	v_exp_f32_e32 v111, v63
	v_cvt_pk_bf16_f32 v52, v64, v65
	v_cvt_pk_bf16_f32 v53, v66, v67
	v_cvt_pk_bf16_f32 v54, v68, v69
	v_cvt_pk_bf16_f32 v55, v70, v71
	v_cvt_pk_bf16_f32 v48, v96, v97
	v_cvt_pk_bf16_f32 v49, v98, v99
	v_cvt_pk_bf16_f32 v50, v100, v101
	v_cvt_pk_bf16_f32 v51, v102, v103
	v_cvt_pk_bf16_f32 v60, v72, v73
	v_cvt_pk_bf16_f32 v61, v74, v75
	v_cvt_pk_bf16_f32 v62, v76, v77
	v_cvt_pk_bf16_f32 v63, v78, v79
	v_cvt_pk_bf16_f32 v56, v104, v105
	v_cvt_pk_bf16_f32 v57, v106, v107
	v_cvt_pk_bf16_f32 v58, v108, v109
	s_and_b64 vcc, exec, s[8:9]
	v_cvt_pk_bf16_f32 v59, v110, v111
	s_cbranch_vccnz .LBB0_872
	ds_read_b128 v[240:243], v115 offset:36864
	ds_read_b128 v[244:247], v115 offset:36896
	ds_read_b128 v[248:251], v115 offset:36928
	ds_read_b128 v[252:255], v115 offset:36960
	s_waitcnt lgkmcnt(3)
	v_mfma_f32_32x32x16_bf16 v[0:15], v[240:243], v[52:55], v[0:15]
	ds_read_b128 v[240:243], v115 offset:41472
	s_waitcnt lgkmcnt(3)
	v_mfma_f32_32x32x16_bf16 v[0:15], v[244:247], v[60:63], v[0:15]
	ds_read_b128 v[244:247], v115 offset:41504
	s_waitcnt lgkmcnt(3)
	v_mfma_f32_32x32x16_bf16 v[0:15], v[248:251], v[48:51], v[0:15]
	ds_read_b128 v[248:251], v115 offset:41536
	s_waitcnt lgkmcnt(3)
	v_mfma_f32_32x32x16_bf16 v[0:15], v[252:255], v[56:59], v[0:15]
	ds_read_b128 v[252:255], v115 offset:41568
	s_waitcnt lgkmcnt(3)
	v_mfma_f32_32x32x16_bf16 v[16:31], v[240:243], v[52:55], v[16:31]
	s_waitcnt lgkmcnt(2)
	v_mfma_f32_32x32x16_bf16 v[16:31], v[244:247], v[60:63], v[16:31]
	s_waitcnt lgkmcnt(1)
	v_mfma_f32_32x32x16_bf16 v[16:31], v[248:251], v[48:51], v[16:31]
	s_waitcnt lgkmcnt(0)
	v_mfma_f32_32x32x16_bf16 v[16:31], v[252:255], v[56:59], v[16:31]
	s_nop 7
.LBB0_872:
	s_waitcnt lgkmcnt(0)
	s_barrier
	s_barrier
	s_and_b64 vcc, exec, s[6:7]
	s_cbranch_vccnz .LBB0_874
	ds_read_b128 v[240:243], v115 offset:36864
	ds_read_b128 v[244:247], v115 offset:36896
	ds_read_b128 v[248:251], v115 offset:36928
	ds_read_b128 v[252:255], v115 offset:36960
	s_waitcnt lgkmcnt(3)
	v_mfma_f32_32x32x16_bf16 v[0:15], v[240:243], v[52:55], v[0:15]
	ds_read_b128 v[240:243], v115 offset:41472
	s_waitcnt lgkmcnt(3)
	v_mfma_f32_32x32x16_bf16 v[0:15], v[244:247], v[60:63], v[0:15]
	ds_read_b128 v[244:247], v115 offset:41504
	s_waitcnt lgkmcnt(3)
	v_mfma_f32_32x32x16_bf16 v[0:15], v[248:251], v[48:51], v[0:15]
	ds_read_b128 v[248:251], v115 offset:41536
	s_waitcnt lgkmcnt(3)
	v_mfma_f32_32x32x16_bf16 v[0:15], v[252:255], v[56:59], v[0:15]
	ds_read_b128 v[252:255], v115 offset:41568
	s_waitcnt lgkmcnt(3)
	v_mfma_f32_32x32x16_bf16 v[16:31], v[240:243], v[52:55], v[16:31]
	s_waitcnt lgkmcnt(2)
	v_mfma_f32_32x32x16_bf16 v[16:31], v[244:247], v[60:63], v[16:31]
	s_waitcnt lgkmcnt(1)
	v_mfma_f32_32x32x16_bf16 v[16:31], v[248:251], v[48:51], v[16:31]
	s_waitcnt lgkmcnt(0)
	v_mfma_f32_32x32x16_bf16 v[16:31], v[252:255], v[56:59], v[16:31]
	s_nop 7

.LBB0_876:
	v_exp_f32_e32 v48, v48
	v_exp_f32_e32 v49, v49
	v_exp_f32_e32 v64, v32
	v_exp_f32_e32 v65, v33
	v_exp_f32_e32 v50, v50
	v_exp_f32_e32 v51, v51
	v_exp_f32_e32 v66, v34
	v_exp_f32_e32 v67, v35
	v_exp_f32_e32 v52, v52
	v_exp_f32_e32 v53, v53
	v_exp_f32_e32 v68, v36
	v_exp_f32_e32 v69, v37
	v_exp_f32_e32 v54, v54
	v_exp_f32_e32 v55, v55
	v_exp_f32_e32 v70, v38
	v_exp_f32_e32 v71, v39
	v_exp_f32_e32 v56, v56
	v_exp_f32_e32 v57, v57
	v_exp_f32_e32 v72, v40
	v_exp_f32_e32 v73, v41
	v_exp_f32_e32 v58, v58
	v_exp_f32_e32 v59, v59
	v_exp_f32_e32 v74, v42
	v_exp_f32_e32 v75, v43
	v_exp_f32_e32 v60, v60
	v_exp_f32_e32 v61, v61
	v_exp_f32_e32 v76, v44
	v_exp_f32_e32 v77, v45
	v_exp_f32_e32 v62, v62
	v_exp_f32_e32 v63, v63
	v_exp_f32_e32 v78, v46
	v_exp_f32_e32 v79, v47
	v_cvt_pk_bf16_f32 v36, v48, v49
	v_cvt_pk_bf16_f32 v37, v50, v51
	v_cvt_pk_bf16_f32 v38, v52, v53
	v_cvt_pk_bf16_f32 v39, v54, v55
	v_cvt_pk_bf16_f32 v32, v64, v65
	v_cvt_pk_bf16_f32 v33, v66, v67
	v_cvt_pk_bf16_f32 v34, v68, v69
	v_cvt_pk_bf16_f32 v35, v70, v71
	v_cvt_pk_bf16_f32 v44, v56, v57
	v_cvt_pk_bf16_f32 v45, v58, v59
	v_cvt_pk_bf16_f32 v46, v60, v61
	v_cvt_pk_bf16_f32 v47, v62, v63
	v_cvt_pk_bf16_f32 v40, v72, v73
	v_cvt_pk_bf16_f32 v41, v74, v75
	v_cvt_pk_bf16_f32 v42, v76, v77
	s_and_b64 vcc, exec, s[8:9]
	v_cvt_pk_bf16_f32 v43, v78, v79
	s_cbranch_vccnz .LBB0_878
	ds_read_b128 v[240:243], v115 offset:18432
	ds_read_b128 v[244:247], v115 offset:18464
	ds_read_b128 v[248:251], v115 offset:18496
	ds_read_b128 v[252:255], v115 offset:18528
	s_waitcnt lgkmcnt(3)
	v_mfma_f32_32x32x16_bf16 v[0:15], v[240:243], v[36:39], v[0:15]
	ds_read_b128 v[240:243], v115 offset:23040
	s_waitcnt lgkmcnt(3)
	v_mfma_f32_32x32x16_bf16 v[0:15], v[244:247], v[44:47], v[0:15]
	ds_read_b128 v[244:247], v115 offset:23072
	s_waitcnt lgkmcnt(3)
	v_mfma_f32_32x32x16_bf16 v[0:15], v[248:251], v[32:35], v[0:15]
	ds_read_b128 v[248:251], v115 offset:23104
	s_waitcnt lgkmcnt(3)
	v_mfma_f32_32x32x16_bf16 v[0:15], v[252:255], v[40:43], v[0:15]
	ds_read_b128 v[252:255], v115 offset:23136
	s_waitcnt lgkmcnt(3)
	v_mfma_f32_32x32x16_bf16 v[16:31], v[240:243], v[36:39], v[16:31]
	s_waitcnt lgkmcnt(2)
	v_mfma_f32_32x32x16_bf16 v[16:31], v[244:247], v[44:47], v[16:31]
	s_waitcnt lgkmcnt(1)
	v_mfma_f32_32x32x16_bf16 v[16:31], v[248:251], v[32:35], v[16:31]
	s_waitcnt lgkmcnt(0)
	v_mfma_f32_32x32x16_bf16 v[16:31], v[252:255], v[40:43], v[16:31]
	s_nop 7
.LBB0_878:
	s_waitcnt lgkmcnt(0)
	s_barrier
	s_barrier
	s_and_b64 vcc, exec, s[6:7]
	s_cbranch_vccnz .LBB0_857
	ds_read_b128 v[240:243], v115 offset:18432
	ds_read_b128 v[244:247], v115 offset:18464
	ds_read_b128 v[248:251], v115 offset:18496
	ds_read_b128 v[252:255], v115 offset:18528
	s_waitcnt lgkmcnt(3)
	v_mfma_f32_32x32x16_bf16 v[0:15], v[240:243], v[36:39], v[0:15]
	ds_read_b128 v[240:243], v115 offset:23040
	s_waitcnt lgkmcnt(3)
	v_mfma_f32_32x32x16_bf16 v[0:15], v[244:247], v[44:47], v[0:15]
	ds_read_b128 v[244:247], v115 offset:23072
	s_waitcnt lgkmcnt(3)
	v_mfma_f32_32x32x16_bf16 v[0:15], v[248:251], v[32:35], v[0:15]
	ds_read_b128 v[248:251], v115 offset:23104
	s_waitcnt lgkmcnt(3)
	v_mfma_f32_32x32x16_bf16 v[0:15], v[252:255], v[40:43], v[0:15]
	ds_read_b128 v[252:255], v115 offset:23136
	s_waitcnt lgkmcnt(3)
	v_mfma_f32_32x32x16_bf16 v[16:31], v[240:243], v[36:39], v[16:31]
	s_waitcnt lgkmcnt(2)
	v_mfma_f32_32x32x16_bf16 v[16:31], v[244:247], v[44:47], v[16:31]
	s_waitcnt lgkmcnt(1)
	v_mfma_f32_32x32x16_bf16 v[16:31], v[248:251], v[32:35], v[16:31]
	s_waitcnt lgkmcnt(0)
	v_mfma_f32_32x32x16_bf16 v[16:31], v[252:255], v[40:43], v[16:31]
	s_nop 7
	s_branch .LBB0_857
